# speedup vs baseline: 1.0076x; 1.0076x over previous
; __device__ __forceinline__ int otid() { int t = threadIdx.x; asm volatile("" : "+v"(t)); return t; }
;   #define STAGE(P,BASE,LD,br,kt) do{long _g=(long)(br)*LD+(long)(kt)*BK; \
;     _Pragma("unroll") for(int _i=0;_i<2;++_i){ \
;       __builtin_amdgcn_global_load_lds((const unsigned*)(BASE+_g+(long)sR[_i]*LD+sC[_i]), \
;         LDSP(unsigned,(char*)(P)+wid*1024+_i*8192),16,0,0);}}while(0)
;   #define WAIT_V(n) asm volatile("s_waitcnt vmcnt(" #n ")":::"memory")
;   #define BAR __builtin_amdgcn_s_barrier()
; template <class Epi>
; __device__ __forceinline__ void gemm_tile8(const u16* __restrict__ A, long lda, const u16* __restrict__ Bt, long ldb, int K, char* shmc, Epi epi){
;     ...
;   const int tid = otid();
;   int wid=__builtin_amdgcn_readfirstlane(tid>>6),lane=tid&63,wr=wid>>2,wc=wid&3,fr=lane&15,fq=lane>>4;
;   int sR[2], sC[2];
; #pragma unroll
;   for(int i=0;i<2;++i) stage_rc8(wid*1024+lane*16+i*8192, sR[i], sC[i]);
;   const int brow=0, bcol=0;
;   f32x4 acc[2][2][4][2];
; #pragma unroll
;   for(int a=0;a<2;++a)
; #pragma unroll
;     for(int b=0;b<2;++b)
; #pragma unroll
;       for(int m=0;m<4;++m)
; #pragma unroll
;         for(int n=0;n<2;++n) acc[a][b][m][n]=f32x4{0,0,0,0};
;   s16x8 At[4][2],B0[2][2],B1[2][2];
;   int nt=K/BK;
;   STAGE(SB(0,0),Bt,ldb,bcol,0); STAGE(SA(0,0),A,lda,brow,0);
;   STAGE(SB(0,1),Bt,ldb,bcol+HALF,0); STAGE(SA(0,1),A,lda,brow+HALF,0);
;   if(wr==1)BAR;
;   WAIT_V(4); BAR;
.LBB0_48:
	s_lshl_b32 s6, s4, 3
	s_and_b32 s6, s6, 8
	s_bfe_u32 s7, s4, 0x30003
	s_or_b32 s6, s6, s7
	s_lshl_b32 s7, s4, 1
	s_and_b32 s7, s7, 12
	s_bfe_u32 s8, s4, 0x20006
	s_or_b32 s7, s7, s8
	s_and_b32 s8, s4, 0xffffff00
	s_lshl_b32 s7, s7, 4
	s_or_b32 s7, s7, s8
	s_or_b32 s6, s7, s6
	s_cmpk_gt_i32 s6, 0x3ff
	s_cbranch_scc1 .LBB0_47
	s_ashr_i32 s7, s6, 31
	s_lshr_b32 s7, s7, 24
	s_add_i32 s7, s6, s7
	s_ashr_i32 s8, s7, 8
	s_lshl_b32 s8, s8, 4
	s_sub_i32 s9, 64, s8
	s_min_i32 s9, s9, 16
	s_abs_i32 s10, s9
	v_cvt_f32_u32_e32 v0, s10
	s_sub_i32 s12, 0, s10
	s_and_b32 s7, s7, 0xffffff00
	s_sub_i32 s7, s6, s7
	v_rcp_iflag_f32_e32 v0, v0
	s_abs_i32 s6, s7
	s_xor_b32 s11, s7, s9
	s_ashr_i32 s11, s11, 31
	v_mul_f32_e32 v0, 0x4f7ffffe, v0
	v_cvt_u32_f32_e32 v0, v0
	v_readlane_b32 s16, v246, 57
	v_readlane_b32 s20, v246, 61
	v_readlane_b32 s21, v246, 62
	v_readfirstlane_b32 s13, v0
	s_mul_i32 s12, s12, s13
	s_mul_hi_u32 s12, s13, s12
	s_add_i32 s13, s13, s12
	s_mul_hi_u32 s12, s6, s13
	s_mul_i32 s13, s12, s10
	s_sub_i32 s6, s6, s13
	s_add_i32 s14, s12, 1
	s_sub_i32 s13, s6, s10
	s_cmp_ge_u32 s6, s10
	s_cselect_b32 s12, s14, s12
	s_cselect_b32 s6, s13, s6
	s_add_i32 s13, s12, 1
	s_cmp_ge_u32 s6, s10
	s_cselect_b32 s6, s13, s12
	s_xor_b32 s6, s6, s11
	s_sub_i32 s6, s6, s11
	s_mul_i32 s9, s6, s9
	s_sub_i32 s7, s7, s9
	s_add_i32 s7, s7, s8
	s_lshl_b32 s8, s7, 8
	s_ashr_i32 s9, s8, 31
	s_lshl_b64 s[12:13], s[8:9], 13
	s_add_u32 s10, s20, s12
	s_addc_u32 s11, s21, s13
	s_ashr_i32 s7, s6, 31
	s_lshl_b64 s[14:15], s[6:7], 21
	v_mov_b32_e32 v32, v204
	v_readlane_b32 s17, v246, 58
	s_add_u32 s16, s2, s14
	v_readlane_b32 s18, v246, 59
	v_readfirstlane_b32 s7, v32
	v_readlane_b32 s19, v246, 60
	s_addc_u32 s17, s3, s15
	s_ashr_i32 s9, s7, 6
	v_lshlrev_b32_e32 v0, 4, v32
	s_lshl_b32 s18, s9, 10
	v_and_b32_e32 v0, 0x3f0, v0
	s_bfe_i32 s19, s9, 0x10015
	v_or_b32_e32 v1, s18, v0
	s_lshr_b32 s19, s19, 22
	v_add_u32_e32 v0, s19, v1
	v_ashrrev_i32_e32 v2, 10, v0
	v_mul_i32_i24_e32 v0, 0x400, v2
	v_sub_u32_e32 v0, v1, v0
	v_lshrrev_b32_e32 v3, 4, v0
	v_bitop3_b32 v3, v3, v0, 32 bitop3:0x6c
	v_ashrrev_i32_e32 v4, 31, v3
	v_lshrrev_b32_e32 v4, 26, v4
	v_add_u32_e32 v4, v3, v4
	v_ashrrev_i32_e32 v5, 6, v4
	v_and_b32_e32 v4, 0xc0, v4
	v_lshlrev_b32_e32 v0, 3, v2
	v_lshlrev_b32_e32 v2, 5, v2
	v_sub_u32_e32 v3, v3, v4
	v_and_b32_e32 v2, 32, v2
	v_ashrrev_i16_sdwa v3, v215, sext(v3) dst_sel:DWORD dst_unused:UNUSED_PAD src0_sel:DWORD src1_sel:BYTE_0
	v_add_u32_e32 v1, 0x2000, v1
	v_add_u32_sdwa v130, v2, sext(v3) dst_sel:DWORD dst_unused:UNUSED_PAD src0_sel:DWORD src1_sel:WORD_0
	v_ashrrev_i32_e32 v2, 31, v1
	v_lshrrev_b32_e32 v2, 22, v2
	v_add_u32_e32 v2, v1, v2
	v_ashrrev_i32_e32 v3, 10, v2
	v_mul_i32_i24_e32 v2, 0x400, v3
	v_sub_u32_e32 v1, v1, v2
	v_lshrrev_b32_e32 v2, 4, v1
	v_bitop3_b32 v1, v2, v1, 32 bitop3:0x6c
	v_ashrrev_i32_e32 v4, 31, v1
	v_lshrrev_b32_e32 v4, 26, v4
	v_and_b32_e32 v0, -16, v0
	v_add_u32_e32 v4, v1, v4
	v_add_u32_e32 v0, v5, v0
	v_ashrrev_i32_e32 v5, 6, v4
	v_and_b32_e32 v4, 0xffc0, v4
	v_sub_u32_e32 v1, v1, v4
	v_lshrrev_b16_e32 v4, 7, v1
	v_and_b32_e32 v4, 1, v4
	v_lshlrev_b32_e32 v2, 3, v3
	v_lshlrev_b32_e32 v3, 5, v3
	v_add_u16_e32 v1, v1, v4
	v_and_b32_e32 v2, -16, v2
	v_and_b32_e32 v3, 32, v3
	v_ashrrev_i16_sdwa v1, v215, sext(v1) dst_sel:DWORD dst_unused:UNUSED_PAD src0_sel:DWORD src1_sel:BYTE_0
	v_add_u32_e32 v2, v5, v2
	v_add_u32_sdwa v132, v3, sext(v1) dst_sel:DWORD dst_unused:UNUSED_PAD src0_sel:DWORD src1_sel:WORD_0
	v_ashrrev_i32_e32 v1, 31, v0
	v_lshlrev_b64 v[134:135], 13, v[0:1]
	v_ashrrev_i32_e32 v131, 31, v130
	v_ashrrev_i32_e32 v3, 31, v2
	s_add_i32 s19, s18, 0x10000
	v_lshl_add_u64 v[4:5], s[16:17], 0, v[134:135]
	v_lshlrev_b64 v[0:1], 1, v[130:131]
	v_lshlrev_b64 v[136:137], 13, v[2:3]
	v_ashrrev_i32_e32 v133, 31, v132
	s_ashr_i32 s30, s7, 8
	v_lshl_add_u64 v[4:5], v[4:5], 0, v[0:1]
	s_mov_b32 m0, s19
	v_lshl_add_u64 v[6:7], s[16:17], 0, v[136:137]
	v_lshlrev_b64 v[2:3], 1, v[132:133]
	s_add_i32 s20, s18, 0x12000
	s_add_i32 s21, s18, 0x2000
	global_load_lds_dwordx4 v[4:5], off
	v_lshl_add_u64 v[6:7], v[6:7], 0, v[2:3]
	s_mov_b32 m0, s20
	v_lshl_add_u64 v[8:9], s[10:11], 0, v[134:135]
	s_add_u32 s24, s16, 0x100000
	v_readlane_b32 s22, v246, 63
	global_load_lds_dwordx4 v[6:7], off
	v_lshl_add_u64 v[10:11], v[8:9], 0, v[0:1]
	s_mov_b32 m0, s18
	v_lshl_add_u64 v[8:9], s[10:11], 0, v[136:137]
	s_addc_u32 s25, s17, 0
	v_readlane_b32 s23, v245, 0
	global_load_lds_dwordx4 v[10:11], off
	v_lshl_add_u64 v[8:9], v[8:9], 0, v[2:3]
	s_mov_b32 m0, s21
	s_add_i32 s22, s18, 0x14000
	v_lshl_add_u64 v[12:13], s[24:25], 0, v[134:135]
	global_load_lds_dwordx4 v[8:9], off
	v_lshl_add_u64 v[12:13], v[12:13], 0, v[0:1]
	s_mov_b32 m0, s22
	s_add_i32 s23, s18, 0x16000
	global_load_lds_dwordx4 v[12:13], off
	v_lshl_add_u64 v[12:13], s[24:25], 0, v[136:137]
	s_add_u32 s26, s10, 0x100000
	v_lshl_add_u64 v[12:13], v[12:13], 0, v[2:3]
	s_mov_b32 m0, s23
	s_addc_u32 s27, s11, 0
	global_load_lds_dwordx4 v[12:13], off
	s_add_i32 s24, s18, 0x4000
	v_lshl_add_u64 v[12:13], s[26:27], 0, v[134:135]
	v_lshl_add_u64 v[12:13], v[12:13], 0, v[0:1]
	s_mov_b32 m0, s24
	s_add_i32 s25, s18, 0x6000
	global_load_lds_dwordx4 v[12:13], off
	v_lshl_add_u64 v[12:13], s[26:27], 0, v[136:137]
	v_lshl_add_u64 v[12:13], v[12:13], 0, v[2:3]
	s_mov_b32 m0, s25
	s_cmp_lg_u32 s30, 1
	global_load_lds_dwordx4 v[12:13], off
	s_cbranch_scc1 .LBB0_51
	s_barrier
	s_setprio 1

;   #define STAGE(P,BASE,LD,br,kt) do{long _g=(long)(br)*LD+(long)(kt)*BK; \
;     _Pragma("unroll") for(int _i=0;_i<2;++_i){ \
;       __builtin_amdgcn_global_load_lds((const unsigned*)(BASE+_g+(long)sR[_i]*LD+sC[_i]), \
;         LDSP(unsigned,(char*)(P)+wid*1024+_i*8192),16,0,0);}}while(0)
;   #define LDA(dst,b,h) _Pragma("unroll") for(int m=0;m<4;++m) _Pragma("unroll") for(int k=0;k<2;++k) \
;     dst[m][k]=*reinterpret_cast<const s16x8*>((char*)SA(b,h)+lds_byte8(wr*64+m*16+fr,k*32+fq*8))
;   #define LDB(dst,b,h) _Pragma("unroll") for(int n=0;n<2;++n) _Pragma("unroll") for(int k=0;k<2;++k) \
;     dst[n][k]=*reinterpret_cast<const s16x8*>((char*)SB(b,h)+lds_byte8(wc*32+n*16+fr,k*32+fq*8))
;   #define MMA(ai,bj,At,Bt) do{__builtin_amdgcn_s_setprio(1); \
;     _Pragma("unroll") for(int m=0;m<4;++m) _Pragma("unroll") for(int n=0;n<2;++n) _Pragma("unroll") for(int k=0;k<2;++k) \
;       acc[ai][bj][m][n]=__builtin_amdgcn_mfma_f32_16x16x32_bf16(Bt[n][k],At[m][k],acc[ai][bj][m][n],0,0,0); \
;     __builtin_amdgcn_s_setprio(0);}while(0)
;   #define WAIT_V(n) asm volatile("s_waitcnt vmcnt(" #n ")":::"memory")
;   #define WAIT_L(n) asm volatile("s_waitcnt lgkmcnt(" #n ")":::"memory")
;   #define BAR __builtin_amdgcn_s_barrier()
;   #define SCHED __builtin_amdgcn_sched_barrier(0)
; template <class Epi>
; __device__ __forceinline__ void gemm_tile8(const u16* __restrict__ A, long lda, const u16* __restrict__ Bt, long ldb, int K, char* shmc, Epi epi){
;     ...
;   for(int t=0;t<nt-2;t+=2){
;     LDB(B0,0,0); SCHED; LDA(At,0,0); STAGE(SA(1,1),A,lda,brow+HALF,t+1);
;     WAIT_L(8); BAR; WAIT_L(0); MMA(0,0,At,B0); BAR; SCHED;
;     LDB(B1,0,1); STAGE(SB(0,0),Bt,ldb,bcol,t+2);
;     BAR; WAIT_L(0); MMA(0,1,At,B1); BAR;
;     LDA(At,0,1); STAGE(SA(0,0),A,lda,brow,t+2);
;     BAR; WAIT_L(0); MMA(1,0,At,B0); BAR; SCHED;
;     STAGE(SB(0,1),Bt,ldb,bcol+HALF,t+2);
;     WAIT_V(6); BAR; MMA(1,1,At,B1); BAR;
.LBB0_52:
	ds_read_b128 v[156:159], v152
	ds_read_b128 v[160:163], v152 offset:1024
	ds_read_b128 v[164:167], v152 offset:2048
	ds_read_b128 v[168:171], v152 offset:3072
	v_lshl_add_u64 v[234:235], v[142:143], 0, s[12:13]
	s_mov_b32 m0, s35
	v_add_u32_e32 v153, s30, v151
	v_add_u32_e32 v154, s31, v151
	v_add_u32_e32 v155, s34, v151
	v_lshl_add_u64 v[218:219], v[234:235], 0, s[36:37]
	v_lshl_add_u64 v[236:237], v[144:145], 0, s[12:13]
	ds_read_b128 v[172:175], v147
	ds_read_b128 v[176:179], v147 offset:1024
	ds_read_b128 v[180:183], v153
	ds_read_b128 v[184:187], v153 offset:1024
	ds_read_b128 v[188:191], v154
	ds_read_b128 v[192:195], v154 offset:1024
	ds_read_b128 v[196:199], v155
	ds_read_b128 v[200:203], v155 offset:1024
	global_load_lds_dwordx4 v[218:219], off
	v_lshl_add_u64 v[218:219], v[236:237], 0, s[36:37]
	s_mov_b32 m0, s14
	s_nop 0
	global_load_lds_dwordx4 v[218:219], off
	s_waitcnt lgkmcnt(8)
	s_barrier
	s_waitcnt lgkmcnt(0)
	s_waitcnt lgkmcnt(0)
	v_mfma_f32_16x16x32_bf16 v[126:129], v[156:159], v[172:175], v[126:129]
	v_mfma_f32_16x16x32_bf16 v[122:125], v[164:167], v[172:175], v[122:125]
	v_mfma_f32_16x16x32_bf16 v[118:121], v[156:159], v[180:183], v[118:121]
	v_mfma_f32_16x16x32_bf16 v[114:117], v[164:167], v[180:183], v[114:117]
	v_mfma_f32_16x16x32_bf16 v[110:113], v[156:159], v[188:191], v[110:113]
	v_mfma_f32_16x16x32_bf16 v[106:109], v[164:167], v[188:191], v[106:109]
	v_mfma_f32_16x16x32_bf16 v[102:105], v[156:159], v[196:199], v[102:105]
	v_mfma_f32_16x16x32_bf16 v[98:101], v[164:167], v[196:199], v[98:101]
	v_mfma_f32_16x16x32_bf16 v[126:129], v[160:163], v[176:179], v[126:129]
	v_mfma_f32_16x16x32_bf16 v[122:125], v[168:171], v[176:179], v[122:125]
	v_mfma_f32_16x16x32_bf16 v[118:121], v[160:163], v[184:187], v[118:121]
	v_mfma_f32_16x16x32_bf16 v[114:117], v[168:171], v[184:187], v[114:117]
	v_mfma_f32_16x16x32_bf16 v[110:113], v[160:163], v[192:195], v[110:113]
	v_mfma_f32_16x16x32_bf16 v[106:109], v[168:171], v[192:195], v[106:109]
	v_mfma_f32_16x16x32_bf16 v[102:105], v[160:163], v[200:203], v[102:105]
	v_mfma_f32_16x16x32_bf16 v[98:101], v[168:171], v[200:203], v[98:101]
	s_barrier
	v_lshl_add_u64 v[238:239], v[138:139], 0, s[12:13]
	s_mov_b32 m0, s19
	v_lshl_add_u64 v[240:241], v[238:239], 0, s[38:39]
	ds_read_b128 v[218:221], v150
	ds_read_b128 v[222:225], v150 offset:1024
	ds_read_b128 v[226:229], v150 offset:2048
	ds_read_b128 v[230:233], v150 offset:3072
	global_load_lds_dwordx4 v[240:241], off
	v_lshl_add_u64 v[240:241], v[140:141], 0, s[12:13]
	v_lshl_add_u64 v[242:243], v[240:241], 0, s[38:39]
	s_mov_b32 m0, s20
	s_nop 0
	global_load_lds_dwordx4 v[242:243], off
	s_barrier
	s_waitcnt lgkmcnt(0)
	s_waitcnt lgkmcnt(0)
	v_mfma_f32_16x16x32_bf16 v[94:97], v[218:221], v[172:175], v[94:97]
	v_mfma_f32_16x16x32_bf16 v[90:93], v[226:229], v[172:175], v[90:93]
	v_mfma_f32_16x16x32_bf16 v[86:89], v[218:221], v[180:183], v[86:89]
	v_mfma_f32_16x16x32_bf16 v[82:85], v[226:229], v[180:183], v[82:85]
	v_mfma_f32_16x16x32_bf16 v[78:81], v[218:221], v[188:191], v[78:81]
	v_mfma_f32_16x16x32_bf16 v[74:77], v[226:229], v[188:191], v[74:77]
	v_mfma_f32_16x16x32_bf16 v[70:73], v[218:221], v[196:199], v[70:73]
	v_mfma_f32_16x16x32_bf16 v[66:69], v[226:229], v[196:199], v[66:69]
	v_mfma_f32_16x16x32_bf16 v[94:97], v[222:225], v[176:179], v[94:97]
	v_mfma_f32_16x16x32_bf16 v[90:93], v[230:233], v[176:179], v[90:93]
	v_mfma_f32_16x16x32_bf16 v[86:89], v[222:225], v[184:187], v[86:89]
	v_mfma_f32_16x16x32_bf16 v[82:85], v[230:233], v[184:187], v[82:85]
	v_mfma_f32_16x16x32_bf16 v[78:81], v[222:225], v[192:195], v[78:81]
	v_mfma_f32_16x16x32_bf16 v[74:77], v[230:233], v[192:195], v[74:77]
	v_mfma_f32_16x16x32_bf16 v[70:73], v[222:225], v[200:203], v[70:73]
	v_mfma_f32_16x16x32_bf16 v[66:69], v[230:233], v[200:203], v[66:69]
	s_mov_b32 m0, s18
	v_lshl_add_u64 v[242:243], v[234:235], 0, s[38:39]
	s_barrier
	ds_read_b128 v[172:175], v147 offset:16384
	ds_read_b128 v[176:179], v147 offset:17408
	ds_read_b128 v[180:183], v153 offset:16384
	ds_read_b128 v[184:187], v153 offset:17408
	ds_read_b128 v[188:191], v154 offset:16384
	ds_read_b128 v[192:195], v154 offset:17408
	ds_read_b128 v[196:199], v155 offset:16384
	ds_read_b128 v[200:203], v155 offset:17408
	global_load_lds_dwordx4 v[242:243], off
	v_lshl_add_u64 v[242:243], v[236:237], 0, s[38:39]
	s_mov_b32 m0, s21
	s_nop 0
	global_load_lds_dwordx4 v[242:243], off
	s_barrier
	s_waitcnt lgkmcnt(0)
	s_waitcnt lgkmcnt(0)
	v_mfma_f32_16x16x32_bf16 v[62:65], v[156:159], v[172:175], v[62:65]
	v_mfma_f32_16x16x32_bf16 v[58:61], v[164:167], v[172:175], v[58:61]
	v_mfma_f32_16x16x32_bf16 v[54:57], v[156:159], v[180:183], v[54:57]
	v_mfma_f32_16x16x32_bf16 v[50:53], v[164:167], v[180:183], v[50:53]
	v_mfma_f32_16x16x32_bf16 v[46:49], v[156:159], v[188:191], v[46:49]
	v_mfma_f32_16x16x32_bf16 v[42:45], v[164:167], v[188:191], v[42:45]
	v_mfma_f32_16x16x32_bf16 v[38:41], v[156:159], v[196:199], v[38:41]
	v_mfma_f32_16x16x32_bf16 v[34:37], v[164:167], v[196:199], v[34:37]
	v_mfma_f32_16x16x32_bf16 v[62:65], v[160:163], v[176:179], v[62:65]
	v_mfma_f32_16x16x32_bf16 v[58:61], v[168:171], v[176:179], v[58:61]
	v_mfma_f32_16x16x32_bf16 v[54:57], v[160:163], v[184:187], v[54:57]
	v_mfma_f32_16x16x32_bf16 v[50:53], v[168:171], v[184:187], v[50:53]
	v_mfma_f32_16x16x32_bf16 v[46:49], v[160:163], v[192:195], v[46:49]
	v_mfma_f32_16x16x32_bf16 v[42:45], v[168:171], v[192:195], v[42:45]
	v_mfma_f32_16x16x32_bf16 v[38:41], v[160:163], v[200:203], v[38:41]
	v_mfma_f32_16x16x32_bf16 v[34:37], v[168:171], v[200:203], v[34:37]
	s_barrier
;   #define STAGE(P,BASE,LD,br,kt) do{long _g=(long)(br)*LD+(long)(kt)*BK; \
;     _Pragma("unroll") for(int _i=0;_i<2;++_i){ \
;       __builtin_amdgcn_global_load_lds((const unsigned*)(BASE+_g+(long)sR[_i]*LD+sC[_i]), \
;         LDSP(unsigned,(char*)(P)+wid*1024+_i*8192),16,0,0);}}while(0)
;   #define LDA(dst,b,h) _Pragma("unroll") for(int m=0;m<4;++m) _Pragma("unroll") for(int k=0;k<2;++k) \
;     dst[m][k]=*reinterpret_cast<const s16x8*>((char*)SA(b,h)+lds_byte8(wr*64+m*16+fr,k*32+fq*8))
;   #define LDB(dst,b,h) _Pragma("unroll") for(int n=0;n<2;++n) _Pragma("unroll") for(int k=0;k<2;++k) \
;     dst[n][k]=*reinterpret_cast<const s16x8*>((char*)SB(b,h)+lds_byte8(wc*32+n*16+fr,k*32+fq*8))
;   #define MMA(ai,bj,At,Bt) do{__builtin_amdgcn_s_setprio(1); \
;     _Pragma("unroll") for(int m=0;m<4;++m) _Pragma("unroll") for(int n=0;n<2;++n) _Pragma("unroll") for(int k=0;k<2;++k) \
;       acc[ai][bj][m][n]=__builtin_amdgcn_mfma_f32_16x16x32_bf16(Bt[n][k],At[m][k],acc[ai][bj][m][n],0,0,0); \
;     __builtin_amdgcn_s_setprio(0);}while(0)
;   #define WAIT_V(n) asm volatile("s_waitcnt vmcnt(" #n ")":::"memory")
;   #define WAIT_L(n) asm volatile("s_waitcnt lgkmcnt(" #n ")":::"memory")
;   #define BAR __builtin_amdgcn_s_barrier()
;   #define SCHED __builtin_amdgcn_sched_barrier(0)
; template <class Epi>
; __device__ __forceinline__ void gemm_tile8(const u16* __restrict__ A, long lda, const u16* __restrict__ Bt, long ldb, int K, char* shmc, Epi epi){
;     ...
;     STAGE(SB(0,1),Bt,ldb,bcol+HALF,t+2);
;     WAIT_V(6); BAR; MMA(1,1,At,B1); BAR;
;     LDB(B0,1,0); SCHED; LDA(At,1,0); STAGE(SA(0,1),A,lda,brow+HALF,t+2);
;     WAIT_L(8); BAR; WAIT_L(0); MMA(0,0,At,B0); BAR; SCHED;
;     LDB(B1,1,1); STAGE(SB(1,0),Bt,ldb,bcol,t+3);
;     BAR; WAIT_L(0); MMA(0,1,At,B1); BAR;
;     LDA(At,1,1); STAGE(SA(1,0),A,lda,brow,t+3);
;     BAR; WAIT_L(0); MMA(1,0,At,B0); BAR; SCHED;
	s_mov_b32 m0, s22
	v_lshl_add_u64 v[156:157], v[238:239], 0, s[40:41]
	global_load_lds_dwordx4 v[156:157], off
	v_lshl_add_u64 v[156:157], v[240:241], 0, s[40:41]
	s_mov_b32 m0, s23
	s_nop 0
	global_load_lds_dwordx4 v[156:157], off
	s_waitcnt vmcnt(6)
	s_barrier
	v_mfma_f32_16x16x32_bf16 v[28:31], v[218:221], v[172:175], v[28:31]
	v_mfma_f32_16x16x32_bf16 v[24:27], v[226:229], v[172:175], v[24:27]
	v_mfma_f32_16x16x32_bf16 v[20:23], v[218:221], v[180:183], v[20:23]
	v_mfma_f32_16x16x32_bf16 v[16:19], v[226:229], v[180:183], v[16:19]
	v_mfma_f32_16x16x32_bf16 v[12:15], v[218:221], v[188:191], v[12:15]
	v_mfma_f32_16x16x32_bf16 v[8:11], v[226:229], v[188:191], v[8:11]
	v_mfma_f32_16x16x32_bf16 v[4:7], v[218:221], v[196:199], v[4:7]
	v_mfma_f32_16x16x32_bf16 v[0:3], v[226:229], v[196:199], v[0:3]
	v_mfma_f32_16x16x32_bf16 v[28:31], v[222:225], v[176:179], v[28:31]
	v_mfma_f32_16x16x32_bf16 v[24:27], v[230:233], v[176:179], v[24:27]
	v_mfma_f32_16x16x32_bf16 v[20:23], v[222:225], v[184:187], v[20:23]
	v_mfma_f32_16x16x32_bf16 v[16:19], v[230:233], v[184:187], v[16:19]
	v_mfma_f32_16x16x32_bf16 v[12:15], v[222:225], v[192:195], v[12:15]
	v_mfma_f32_16x16x32_bf16 v[8:11], v[230:233], v[192:195], v[8:11]
	v_mfma_f32_16x16x32_bf16 v[4:7], v[222:225], v[200:203], v[4:7]
	v_mfma_f32_16x16x32_bf16 v[0:3], v[230:233], v[200:203], v[0:3]
	s_barrier
	ds_read_b128 v[156:159], v149
	ds_read_b128 v[160:163], v149 offset:1024
	ds_read_b128 v[164:167], v149 offset:2048
	ds_read_b128 v[168:171], v149 offset:3072
	s_mov_b32 m0, s24
	v_lshl_add_u64 v[218:219], v[234:235], 0, s[40:41]
	ds_read_b128 v[172:175], v147 offset:32768
	ds_read_b128 v[176:179], v147 offset:33792
	ds_read_b128 v[180:183], v153 offset:32768
	ds_read_b128 v[184:187], v153 offset:33792
	ds_read_b128 v[188:191], v154 offset:32768
	ds_read_b128 v[192:195], v154 offset:33792
	ds_read_b128 v[196:199], v155 offset:32768
	ds_read_b128 v[200:203], v155 offset:33792
	global_load_lds_dwordx4 v[218:219], off
	v_lshl_add_u64 v[218:219], v[236:237], 0, s[40:41]
	s_mov_b32 m0, s25
	s_nop 0
	global_load_lds_dwordx4 v[218:219], off
	s_waitcnt lgkmcnt(8)
	s_barrier
	s_waitcnt lgkmcnt(0)
	s_waitcnt lgkmcnt(0)
	v_mfma_f32_16x16x32_bf16 v[126:129], v[156:159], v[172:175], v[126:129]
	v_mfma_f32_16x16x32_bf16 v[122:125], v[164:167], v[172:175], v[122:125]
	v_mfma_f32_16x16x32_bf16 v[118:121], v[156:159], v[180:183], v[118:121]
	v_mfma_f32_16x16x32_bf16 v[114:117], v[164:167], v[180:183], v[114:117]
	v_mfma_f32_16x16x32_bf16 v[110:113], v[156:159], v[188:191], v[110:113]
	v_mfma_f32_16x16x32_bf16 v[106:109], v[164:167], v[188:191], v[106:109]
	v_mfma_f32_16x16x32_bf16 v[102:105], v[156:159], v[196:199], v[102:105]
	v_mfma_f32_16x16x32_bf16 v[98:101], v[164:167], v[196:199], v[98:101]
	v_mfma_f32_16x16x32_bf16 v[126:129], v[160:163], v[176:179], v[126:129]
	v_mfma_f32_16x16x32_bf16 v[122:125], v[168:171], v[176:179], v[122:125]
	v_mfma_f32_16x16x32_bf16 v[118:121], v[160:163], v[184:187], v[118:121]
	v_mfma_f32_16x16x32_bf16 v[114:117], v[168:171], v[184:187], v[114:117]
	v_mfma_f32_16x16x32_bf16 v[110:113], v[160:163], v[192:195], v[110:113]
	v_mfma_f32_16x16x32_bf16 v[106:109], v[168:171], v[192:195], v[106:109]
	v_mfma_f32_16x16x32_bf16 v[102:105], v[160:163], v[200:203], v[102:105]
	v_mfma_f32_16x16x32_bf16 v[98:101], v[168:171], v[200:203], v[98:101]
	s_barrier
	s_mov_b32 m0, s26
	v_lshl_add_u64 v[242:243], v[238:239], 0, s[42:43]
	ds_read_b128 v[218:221], v148
	ds_read_b128 v[222:225], v148 offset:1024
	ds_read_b128 v[226:229], v148 offset:2048
	ds_read_b128 v[230:233], v148 offset:3072
	global_load_lds_dwordx4 v[242:243], off
	v_lshl_add_u64 v[242:243], v[240:241], 0, s[42:43]
	s_mov_b32 m0, s27
	s_nop 0
	global_load_lds_dwordx4 v[242:243], off
	s_barrier
	s_waitcnt lgkmcnt(0)
	s_waitcnt lgkmcnt(0)
	v_mfma_f32_16x16x32_bf16 v[94:97], v[218:221], v[172:175], v[94:97]
	v_mfma_f32_16x16x32_bf16 v[90:93], v[226:229], v[172:175], v[90:93]
	v_mfma_f32_16x16x32_bf16 v[86:89], v[218:221], v[180:183], v[86:89]
	v_mfma_f32_16x16x32_bf16 v[82:85], v[226:229], v[180:183], v[82:85]
	v_mfma_f32_16x16x32_bf16 v[78:81], v[218:221], v[188:191], v[78:81]
	v_mfma_f32_16x16x32_bf16 v[74:77], v[226:229], v[188:191], v[74:77]
	v_mfma_f32_16x16x32_bf16 v[70:73], v[218:221], v[196:199], v[70:73]
	v_mfma_f32_16x16x32_bf16 v[66:69], v[226:229], v[196:199], v[66:69]
	v_mfma_f32_16x16x32_bf16 v[94:97], v[222:225], v[176:179], v[94:97]
	v_mfma_f32_16x16x32_bf16 v[90:93], v[230:233], v[176:179], v[90:93]
	v_mfma_f32_16x16x32_bf16 v[86:89], v[222:225], v[184:187], v[86:89]
	v_mfma_f32_16x16x32_bf16 v[82:85], v[230:233], v[184:187], v[82:85]
	v_mfma_f32_16x16x32_bf16 v[78:81], v[222:225], v[192:195], v[78:81]
	v_mfma_f32_16x16x32_bf16 v[74:77], v[230:233], v[192:195], v[74:77]
	v_mfma_f32_16x16x32_bf16 v[70:73], v[222:225], v[200:203], v[70:73]
	v_mfma_f32_16x16x32_bf16 v[66:69], v[230:233], v[200:203], v[66:69]
	s_mov_b32 m0, s28
	v_lshl_add_u64 v[234:235], v[234:235], 0, s[42:43]
	s_barrier
	ds_read_b128 v[172:175], v147 offset:49152
	ds_read_b128 v[176:179], v147 offset:50176
	ds_read_b128 v[180:183], v153 offset:49152
	ds_read_b128 v[184:187], v153 offset:50176
	ds_read_b128 v[188:191], v154 offset:49152
	ds_read_b128 v[192:195], v154 offset:50176
	ds_read_b128 v[196:199], v155 offset:49152
	ds_read_b128 v[200:203], v155 offset:50176
	global_load_lds_dwordx4 v[234:235], off
	v_lshl_add_u64 v[234:235], v[236:237], 0, s[42:43]
	s_mov_b32 m0, s29
	s_nop 0
	global_load_lds_dwordx4 v[234:235], off
	s_barrier
;   #define STAGE(P,BASE,LD,br,kt) do{long _g=(long)(br)*LD+(long)(kt)*BK; \
;     _Pragma("unroll") for(int _i=0;_i<2;++_i){ \
;       __builtin_amdgcn_global_load_lds((const unsigned*)(BASE+_g+(long)sR[_i]*LD+sC[_i]), \
;         LDSP(unsigned,(char*)(P)+wid*1024+_i*8192),16,0,0);}}while(0)
;   #define LDA(dst,b,h) _Pragma("unroll") for(int m=0;m<4;++m) _Pragma("unroll") for(int k=0;k<2;++k) \
;     dst[m][k]=*reinterpret_cast<const s16x8*>((char*)SA(b,h)+lds_byte8(wr*64+m*16+fr,k*32+fq*8))
;   #define LDB(dst,b,h) _Pragma("unroll") for(int n=0;n<2;++n) _Pragma("unroll") for(int k=0;k<2;++k) \
;     dst[n][k]=*reinterpret_cast<const s16x8*>((char*)SB(b,h)+lds_byte8(wc*32+n*16+fr,k*32+fq*8))
;   #define MMA(ai,bj,At,Bt) do{__builtin_amdgcn_s_setprio(1); \
;     _Pragma("unroll") for(int m=0;m<4;++m) _Pragma("unroll") for(int n=0;n<2;++n) _Pragma("unroll") for(int k=0;k<2;++k) \
;       acc[ai][bj][m][n]=__builtin_amdgcn_mfma_f32_16x16x32_bf16(Bt[n][k],At[m][k],acc[ai][bj][m][n],0,0,0); \
;     __builtin_amdgcn_s_setprio(0);}while(0)
;   #define WAIT_V(n) asm volatile("s_waitcnt vmcnt(" #n ")":::"memory")
;   #define WAIT_L(n) asm volatile("s_waitcnt lgkmcnt(" #n ")":::"memory")
;   #define BAR __builtin_amdgcn_s_barrier()
; template <class Epi>
; __device__ __forceinline__ void gemm_tile8(const u16* __restrict__ A, long lda, const u16* __restrict__ Bt, long ldb, int K, char* shmc, Epi epi){
;     ...
;     STAGE(SB(1,1),Bt,ldb,bcol+HALF,t+3);
;     WAIT_V(6); BAR; MMA(1,1,At,B1); BAR;
;   }
;   { LDB(B0,0,0); LDA(At,0,0); STAGE(SA(1,1),A,lda,brow+HALF,nt-1);
;     BAR; WAIT_L(0); MMA(0,0,At,B0); BAR;
;     LDB(B1,0,1); BAR; WAIT_L(0); MMA(0,1,At,B1); BAR;
;     LDA(At,0,1); WAIT_V(4); BAR; WAIT_L(0); MMA(1,0,At,B0); MMA(1,1,At,B1); BAR; }
	s_waitcnt lgkmcnt(0)
	s_waitcnt lgkmcnt(0)
	v_mfma_f32_16x16x32_bf16 v[62:65], v[156:159], v[172:175], v[62:65]
	v_mfma_f32_16x16x32_bf16 v[58:61], v[164:167], v[172:175], v[58:61]
	v_mfma_f32_16x16x32_bf16 v[54:57], v[156:159], v[180:183], v[54:57]
	v_mfma_f32_16x16x32_bf16 v[50:53], v[164:167], v[180:183], v[50:53]
	v_mfma_f32_16x16x32_bf16 v[46:49], v[156:159], v[188:191], v[46:49]
	v_mfma_f32_16x16x32_bf16 v[42:45], v[164:167], v[188:191], v[42:45]
	v_mfma_f32_16x16x32_bf16 v[38:41], v[156:159], v[196:199], v[38:41]
	v_mfma_f32_16x16x32_bf16 v[34:37], v[164:167], v[196:199], v[34:37]
	v_mfma_f32_16x16x32_bf16 v[62:65], v[160:163], v[176:179], v[62:65]
	v_mfma_f32_16x16x32_bf16 v[58:61], v[168:171], v[176:179], v[58:61]
	v_mfma_f32_16x16x32_bf16 v[54:57], v[160:163], v[184:187], v[54:57]
	v_mfma_f32_16x16x32_bf16 v[50:53], v[168:171], v[184:187], v[50:53]
	v_mfma_f32_16x16x32_bf16 v[46:49], v[160:163], v[192:195], v[46:49]
	v_mfma_f32_16x16x32_bf16 v[42:45], v[168:171], v[192:195], v[42:45]
	v_mfma_f32_16x16x32_bf16 v[38:41], v[160:163], v[200:203], v[38:41]
	v_mfma_f32_16x16x32_bf16 v[34:37], v[168:171], v[200:203], v[34:37]
	s_barrier
	s_mov_b32 m0, s16
	v_lshl_add_u64 v[156:157], v[238:239], 0, s[44:45]
	global_load_lds_dwordx4 v[156:157], off
	v_lshl_add_u64 v[156:157], v[240:241], 0, s[44:45]
	s_mov_b32 m0, s17
	s_nop 0
	global_load_lds_dwordx4 v[156:157], off
	s_waitcnt vmcnt(6)
	s_barrier
	v_mfma_f32_16x16x32_bf16 v[28:31], v[218:221], v[172:175], v[28:31]
	v_mfma_f32_16x16x32_bf16 v[24:27], v[226:229], v[172:175], v[24:27]
	v_mfma_f32_16x16x32_bf16 v[20:23], v[218:221], v[180:183], v[20:23]
	v_mfma_f32_16x16x32_bf16 v[16:19], v[226:229], v[180:183], v[16:19]
	v_mfma_f32_16x16x32_bf16 v[12:15], v[218:221], v[188:191], v[12:15]
	v_mfma_f32_16x16x32_bf16 v[8:11], v[226:229], v[188:191], v[8:11]
	v_mfma_f32_16x16x32_bf16 v[4:7], v[218:221], v[196:199], v[4:7]
	v_mfma_f32_16x16x32_bf16 v[0:3], v[226:229], v[196:199], v[0:3]
	v_mfma_f32_16x16x32_bf16 v[28:31], v[222:225], v[176:179], v[28:31]
	v_mfma_f32_16x16x32_bf16 v[24:27], v[230:233], v[176:179], v[24:27]
	v_mfma_f32_16x16x32_bf16 v[20:23], v[222:225], v[184:187], v[20:23]
	v_mfma_f32_16x16x32_bf16 v[16:19], v[230:233], v[184:187], v[16:19]
	v_mfma_f32_16x16x32_bf16 v[12:15], v[222:225], v[192:195], v[12:15]
	v_mfma_f32_16x16x32_bf16 v[8:11], v[230:233], v[192:195], v[8:11]
	v_mfma_f32_16x16x32_bf16 v[4:7], v[222:225], v[200:203], v[4:7]
	v_mfma_f32_16x16x32_bf16 v[0:3], v[230:233], v[200:203], v[0:3]
	s_add_i32 s15, s15, 2
	s_add_u32 s12, s12, 0x100
	s_addc_u32 s13, s13, 0
	s_cmp_lt_u32 s15, 60
	s_barrier
	s_cbranch_scc1 .LBB0_52
	s_add_u32 s10, s10, 0x101f80
	s_addc_u32 s11, s11, 0
	v_lshl_add_u64 v[134:135], s[10:11], 0, v[134:135]
	s_mov_b32 m0, s35
	v_lshl_add_u64 v[130:131], v[130:131], 1, v[134:135]
	ds_read_b128 v[138:141], v152
	ds_read_b128 v[142:145], v152 offset:1024
	ds_read_b128 v[156:159], v152 offset:2048
	ds_read_b128 v[160:163], v152 offset:3072
	ds_read_b128 v[164:167], v147
	ds_read_b128 v[168:171], v147 offset:1024
	ds_read_b128 v[172:175], v153
	ds_read_b128 v[176:179], v153 offset:1024
	ds_read_b128 v[180:183], v154
	ds_read_b128 v[184:187], v154 offset:1024
	ds_read_b128 v[188:191], v155
	ds_read_b128 v[192:195], v155 offset:1024
	global_load_lds_dwordx4 v[130:131], off
	v_lshl_add_u64 v[130:131], s[10:11], 0, v[136:137]
	v_lshl_add_u64 v[130:131], v[132:133], 1, v[130:131]
	s_mov_b32 m0, s14
	s_nop 0
	global_load_lds_dwordx4 v[130:131], off
	s_barrier
	s_waitcnt lgkmcnt(0)
	s_waitcnt lgkmcnt(0)
	v_mfma_f32_16x16x32_bf16 v[126:129], v[138:141], v[164:167], v[126:129]
	v_mfma_f32_16x16x32_bf16 v[122:125], v[156:159], v[164:167], v[122:125]
	v_mfma_f32_16x16x32_bf16 v[118:121], v[138:141], v[172:175], v[118:121]
	v_mfma_f32_16x16x32_bf16 v[114:117], v[156:159], v[172:175], v[114:117]
	v_mfma_f32_16x16x32_bf16 v[110:113], v[138:141], v[180:183], v[110:113]
	v_mfma_f32_16x16x32_bf16 v[106:109], v[156:159], v[180:183], v[106:109]
	v_mfma_f32_16x16x32_bf16 v[102:105], v[138:141], v[188:191], v[102:105]
	v_mfma_f32_16x16x32_bf16 v[98:101], v[156:159], v[188:191], v[98:101]
	v_mfma_f32_16x16x32_bf16 v[126:129], v[142:145], v[168:171], v[126:129]
	v_mfma_f32_16x16x32_bf16 v[122:125], v[160:163], v[168:171], v[122:125]
	v_mfma_f32_16x16x32_bf16 v[118:121], v[142:145], v[176:179], v[118:121]
	v_mfma_f32_16x16x32_bf16 v[114:117], v[160:163], v[176:179], v[114:117]
	v_mfma_f32_16x16x32_bf16 v[110:113], v[142:145], v[184:187], v[110:113]
	v_mfma_f32_16x16x32_bf16 v[106:109], v[160:163], v[184:187], v[106:109]
	v_mfma_f32_16x16x32_bf16 v[102:105], v[142:145], v[192:195], v[102:105]
	v_mfma_f32_16x16x32_bf16 v[98:101], v[160:163], v[192:195], v[98:101]
	s_barrier
	ds_read_b128 v[130:133], v150
	ds_read_b128 v[134:137], v150 offset:1024
	ds_read_b128 v[196:199], v150 offset:2048
	ds_read_b128 v[200:203], v150 offset:3072
	s_barrier
	s_waitcnt lgkmcnt(0)
	s_waitcnt lgkmcnt(0)
	v_mfma_f32_16x16x32_bf16 v[90:93], v[196:199], v[164:167], v[90:93]
	v_mfma_f32_16x16x32_bf16 v[86:89], v[130:133], v[172:175], v[86:89]
	v_mfma_f32_16x16x32_bf16 v[82:85], v[196:199], v[172:175], v[82:85]
	v_mfma_f32_16x16x32_bf16 v[78:81], v[130:133], v[180:183], v[78:81]
	v_mfma_f32_16x16x32_bf16 v[74:77], v[196:199], v[180:183], v[74:77]
	v_mfma_f32_16x16x32_bf16 v[70:73], v[130:133], v[188:191], v[70:73]
	v_mfma_f32_16x16x32_bf16 v[66:69], v[196:199], v[188:191], v[66:69]
	v_mfma_f32_16x16x32_bf16 v[94:97], v[130:133], v[164:167], v[94:97]
	v_mfma_f32_16x16x32_bf16 v[90:93], v[200:203], v[168:171], v[90:93]
	v_mfma_f32_16x16x32_bf16 v[86:89], v[134:137], v[176:179], v[86:89]
	v_mfma_f32_16x16x32_bf16 v[82:85], v[200:203], v[176:179], v[82:85]
	v_mfma_f32_16x16x32_bf16 v[78:81], v[134:137], v[184:187], v[78:81]
	v_mfma_f32_16x16x32_bf16 v[74:77], v[200:203], v[184:187], v[74:77]
	v_mfma_f32_16x16x32_bf16 v[70:73], v[134:137], v[192:195], v[70:73]
	v_mfma_f32_16x16x32_bf16 v[66:69], v[200:203], v[192:195], v[66:69]
	v_mfma_f32_16x16x32_bf16 v[218:221], v[134:137], v[168:171], v[94:97]
	s_barrier
;   #define LDA(dst,b,h) _Pragma("unroll") for(int m=0;m<4;++m) _Pragma("unroll") for(int k=0;k<2;++k) \
;     dst[m][k]=*reinterpret_cast<const s16x8*>((char*)SA(b,h)+lds_byte8(wr*64+m*16+fr,k*32+fq*8))
;   #define LDB(dst,b,h) _Pragma("unroll") for(int n=0;n<2;++n) _Pragma("unroll") for(int k=0;k<2;++k) \
;     dst[n][k]=*reinterpret_cast<const s16x8*>((char*)SB(b,h)+lds_byte8(wc*32+n*16+fr,k*32+fq*8))
;   #define MMA(ai,bj,At,Bt) do{__builtin_amdgcn_s_setprio(1); \
;     _Pragma("unroll") for(int m=0;m<4;++m) _Pragma("unroll") for(int n=0;n<2;++n) _Pragma("unroll") for(int k=0;k<2;++k) \
;       acc[ai][bj][m][n]=__builtin_amdgcn_mfma_f32_16x16x32_bf16(Bt[n][k],At[m][k],acc[ai][bj][m][n],0,0,0); \
;     __builtin_amdgcn_s_setprio(0);}while(0)
;   #define WAIT_V(n) asm volatile("s_waitcnt vmcnt(" #n ")":::"memory")
;   #define WAIT_L(n) asm volatile("s_waitcnt lgkmcnt(" #n ")":::"memory")
;   #define BAR __builtin_amdgcn_s_barrier()
; template <class Epi>
; __device__ __forceinline__ void gemm_tile8(const u16* __restrict__ A, long lda, const u16* __restrict__ Bt, long ldb, int K, char* shmc, Epi epi){
;     ...
;     LDA(At,0,1); WAIT_V(4); BAR; WAIT_L(0); MMA(1,0,At,B0); MMA(1,1,At,B1); BAR; }
;   { LDB(B0,1,0); LDA(At,1,0); WAIT_V(2); BAR; WAIT_L(0); MMA(0,0,At,B0); BAR;
;     LDB(B1,1,1); WAIT_V(0); BAR; WAIT_L(0); MMA(0,1,At,B1); BAR;
	s_nop 0
	ds_read_b128 v[94:97], v147 offset:16384
	ds_read_b128 v[164:167], v147 offset:17408
	ds_read_b128 v[168:171], v153 offset:16384
	ds_read_b128 v[172:175], v153 offset:17408
	ds_read_b128 v[176:179], v154 offset:16384
	ds_read_b128 v[180:183], v154 offset:17408
	ds_read_b128 v[184:187], v155 offset:16384
	ds_read_b128 v[188:191], v155 offset:17408
	s_waitcnt vmcnt(4)
	s_barrier
	s_waitcnt lgkmcnt(0)
	s_waitcnt lgkmcnt(0)
	v_mfma_f32_16x16x32_bf16 v[58:61], v[156:159], v[94:97], v[58:61]
	v_mfma_f32_16x16x32_bf16 v[54:57], v[138:141], v[168:171], v[54:57]
	v_mfma_f32_16x16x32_bf16 v[50:53], v[156:159], v[168:171], v[50:53]
	v_mfma_f32_16x16x32_bf16 v[46:49], v[138:141], v[176:179], v[46:49]
	v_mfma_f32_16x16x32_bf16 v[42:45], v[156:159], v[176:179], v[42:45]
	v_mfma_f32_16x16x32_bf16 v[38:41], v[138:141], v[184:187], v[38:41]
	v_mfma_f32_16x16x32_bf16 v[34:37], v[156:159], v[184:187], v[34:37]
	v_mfma_f32_16x16x32_bf16 v[62:65], v[138:141], v[94:97], v[62:65]
	v_mfma_f32_16x16x32_bf16 v[58:61], v[160:163], v[164:167], v[58:61]
	v_mfma_f32_16x16x32_bf16 v[54:57], v[142:145], v[172:175], v[54:57]
	v_mfma_f32_16x16x32_bf16 v[50:53], v[160:163], v[172:175], v[50:53]
	v_mfma_f32_16x16x32_bf16 v[46:49], v[142:145], v[180:183], v[46:49]
	v_mfma_f32_16x16x32_bf16 v[42:45], v[160:163], v[180:183], v[42:45]
	v_mfma_f32_16x16x32_bf16 v[38:41], v[142:145], v[188:191], v[38:41]
	v_mfma_f32_16x16x32_bf16 v[34:37], v[160:163], v[188:191], v[34:37]
	v_mfma_f32_16x16x32_bf16 v[192:195], v[142:145], v[164:167], v[62:65]
	v_mfma_f32_16x16x32_bf16 v[28:31], v[130:133], v[94:97], v[28:31]
	v_mfma_f32_16x16x32_bf16 v[24:27], v[196:199], v[94:97], v[24:27]
	v_mfma_f32_16x16x32_bf16 v[20:23], v[130:133], v[168:171], v[20:23]
	v_mfma_f32_16x16x32_bf16 v[16:19], v[196:199], v[168:171], v[16:19]
	v_mfma_f32_16x16x32_bf16 v[12:15], v[130:133], v[176:179], v[12:15]
	v_mfma_f32_16x16x32_bf16 v[8:11], v[196:199], v[176:179], v[8:11]
	v_mfma_f32_16x16x32_bf16 v[4:7], v[130:133], v[184:187], v[4:7]
	v_mfma_f32_16x16x32_bf16 v[0:3], v[196:199], v[184:187], v[0:3]
	v_mfma_f32_16x16x32_bf16 v[28:31], v[134:137], v[164:167], v[28:31]
	v_mfma_f32_16x16x32_bf16 v[24:27], v[200:203], v[164:167], v[24:27]
	v_mfma_f32_16x16x32_bf16 v[20:23], v[134:137], v[172:175], v[20:23]
	v_mfma_f32_16x16x32_bf16 v[16:19], v[200:203], v[172:175], v[16:19]
	v_mfma_f32_16x16x32_bf16 v[12:15], v[134:137], v[180:183], v[12:15]
	v_mfma_f32_16x16x32_bf16 v[8:11], v[200:203], v[180:183], v[8:11]
	v_mfma_f32_16x16x32_bf16 v[4:7], v[134:137], v[188:191], v[4:7]
	v_mfma_f32_16x16x32_bf16 v[0:3], v[200:203], v[188:191], v[0:3]
	s_barrier
	ds_read_b128 v[130:133], v149
	ds_read_b128 v[134:137], v149 offset:1024
	ds_read_b128 v[138:141], v149 offset:2048
	ds_read_b128 v[142:145], v149 offset:3072
	ds_read_b128 v[62:65], v147 offset:32768
	ds_read_b128 v[156:159], v147 offset:33792
	ds_read_b128 v[160:163], v153 offset:32768
	ds_read_b128 v[164:167], v153 offset:33792
	ds_read_b128 v[168:171], v154 offset:32768
	ds_read_b128 v[172:175], v154 offset:33792
	ds_read_b128 v[176:179], v155 offset:32768
	ds_read_b128 v[180:183], v155 offset:33792
	s_waitcnt vmcnt(2)
	s_barrier
	s_waitcnt lgkmcnt(0)
	s_waitcnt lgkmcnt(0)
	v_mfma_f32_16x16x32_bf16 v[94:97], v[130:133], v[62:65], v[126:129]
	v_mfma_f32_16x16x32_bf16 v[126:129], v[134:137], v[156:159], v[94:97]
	v_mfma_f32_16x16x32_bf16 v[94:97], v[138:141], v[62:65], v[122:125]
	v_mfma_f32_16x16x32_bf16 v[122:125], v[142:145], v[156:159], v[94:97]
	v_mfma_f32_16x16x32_bf16 v[94:97], v[130:133], v[160:163], v[118:121]
	v_mfma_f32_16x16x32_bf16 v[118:121], v[134:137], v[164:167], v[94:97]
	v_mfma_f32_16x16x32_bf16 v[94:97], v[138:141], v[160:163], v[114:117]
	v_mfma_f32_16x16x32_bf16 v[114:117], v[142:145], v[164:167], v[94:97]
	v_mfma_f32_16x16x32_bf16 v[94:97], v[130:133], v[168:171], v[110:113]
	v_mfma_f32_16x16x32_bf16 v[110:113], v[134:137], v[172:175], v[94:97]
	v_mfma_f32_16x16x32_bf16 v[94:97], v[138:141], v[168:171], v[106:109]
	v_mfma_f32_16x16x32_bf16 v[106:109], v[142:145], v[172:175], v[94:97]
	v_mfma_f32_16x16x32_bf16 v[94:97], v[130:133], v[176:179], v[102:105]
	v_mfma_f32_16x16x32_bf16 v[102:105], v[134:137], v[180:183], v[94:97]
	v_mfma_f32_16x16x32_bf16 v[94:97], v[138:141], v[176:179], v[98:101]
	v_mfma_f32_16x16x32_bf16 v[94:97], v[142:145], v[180:183], v[94:97]
	s_barrier
;   #define LDA(dst,b,h) _Pragma("unroll") for(int m=0;m<4;++m) _Pragma("unroll") for(int k=0;k<2;++k) \
;     dst[m][k]=*reinterpret_cast<const s16x8*>((char*)SA(b,h)+lds_byte8(wr*64+m*16+fr,k*32+fq*8))
;   #define LDB(dst,b,h) _Pragma("unroll") for(int n=0;n<2;++n) _Pragma("unroll") for(int k=0;k<2;++k) \
;     dst[n][k]=*reinterpret_cast<const s16x8*>((char*)SB(b,h)+lds_byte8(wc*32+n*16+fr,k*32+fq*8))
;   #define MMA(ai,bj,At,Bt) do{__builtin_amdgcn_s_setprio(1); \
;     _Pragma("unroll") for(int m=0;m<4;++m) _Pragma("unroll") for(int n=0;n<2;++n) _Pragma("unroll") for(int k=0;k<2;++k) \
;       acc[ai][bj][m][n]=__builtin_amdgcn_mfma_f32_16x16x32_bf16(Bt[n][k],At[m][k],acc[ai][bj][m][n],0,0,0); \
;     __builtin_amdgcn_s_setprio(0);}while(0)
;   #define WAIT_V(n) asm volatile("s_waitcnt vmcnt(" #n ")":::"memory")
;   #define WAIT_L(n) asm volatile("s_waitcnt lgkmcnt(" #n ")":::"memory")
;   #define BAR __builtin_amdgcn_s_barrier()
; template <class Epi>
; __device__ __forceinline__ void gemm_tile8(const u16* __restrict__ A, long lda, const u16* __restrict__ Bt, long ldb, int K, char* shmc, Epi epi){
;     ...
;   { LDB(B0,1,0); LDA(At,1,0); WAIT_V(2); BAR; WAIT_L(0); MMA(0,0,At,B0); BAR;
;     LDB(B1,1,1); WAIT_V(0); BAR; WAIT_L(0); MMA(0,1,At,B1); BAR;
;     LDA(At,1,1); BAR; WAIT_L(0); MMA(1,0,At,B0); MMA(1,1,At,B1); BAR; }
;   if(wr==0)BAR;
	ds_read_b128 v[184:187], v148
	ds_read_b128 v[188:191], v148 offset:1024
	ds_read_b128 v[196:199], v148 offset:2048
	ds_read_b128 v[148:151], v148 offset:3072
	s_waitcnt vmcnt(0)
	s_barrier
	s_waitcnt lgkmcnt(0)
	s_waitcnt lgkmcnt(0)
	v_mfma_f32_16x16x32_bf16 v[98:101], v[184:187], v[62:65], v[218:221]
	v_mfma_f32_16x16x32_bf16 v[62:65], v[196:199], v[62:65], v[90:93]
	v_mfma_f32_16x16x32_bf16 v[90:93], v[148:151], v[156:159], v[62:65]
	v_mfma_f32_16x16x32_bf16 v[62:65], v[184:187], v[160:163], v[86:89]
	v_mfma_f32_16x16x32_bf16 v[86:89], v[188:191], v[164:167], v[62:65]
	v_mfma_f32_16x16x32_bf16 v[62:65], v[196:199], v[160:163], v[82:85]
	v_mfma_f32_16x16x32_bf16 v[82:85], v[148:151], v[164:167], v[62:65]
	v_mfma_f32_16x16x32_bf16 v[62:65], v[184:187], v[168:171], v[78:81]
	v_mfma_f32_16x16x32_bf16 v[78:81], v[188:191], v[172:175], v[62:65]
	v_mfma_f32_16x16x32_bf16 v[62:65], v[196:199], v[168:171], v[74:77]
	v_mfma_f32_16x16x32_bf16 v[74:77], v[148:151], v[172:175], v[62:65]
	v_mfma_f32_16x16x32_bf16 v[62:65], v[184:187], v[176:179], v[70:73]
	v_mfma_f32_16x16x32_bf16 v[70:73], v[188:191], v[180:183], v[62:65]
	v_mfma_f32_16x16x32_bf16 v[62:65], v[196:199], v[176:179], v[66:69]
	v_mfma_f32_16x16x32_bf16 v[98:101], v[188:191], v[156:159], v[98:101]
	v_mfma_f32_16x16x32_bf16 v[62:65], v[148:151], v[180:183], v[62:65]
	s_barrier
	ds_read_b128 v[156:159], v147 offset:49152
	ds_read_b128 v[160:163], v147 offset:50176
	ds_read_b128 v[164:167], v153 offset:49152
	ds_read_b128 v[168:171], v153 offset:50176
	ds_read_b128 v[172:175], v154 offset:49152
	ds_read_b128 v[176:179], v154 offset:50176
	ds_read_b128 v[180:183], v155 offset:49152
	ds_read_b128 v[152:155], v155 offset:50176
	s_barrier
	s_waitcnt lgkmcnt(0)
	s_waitcnt lgkmcnt(0)
	v_mfma_f32_16x16x32_bf16 v[66:69], v[130:133], v[156:159], v[192:195]
	v_mfma_f32_16x16x32_bf16 v[58:61], v[138:141], v[156:159], v[58:61]
	v_mfma_f32_16x16x32_bf16 v[54:57], v[130:133], v[164:167], v[54:57]
	v_mfma_f32_16x16x32_bf16 v[50:53], v[138:141], v[164:167], v[50:53]
	v_mfma_f32_16x16x32_bf16 v[46:49], v[130:133], v[172:175], v[46:49]
	v_mfma_f32_16x16x32_bf16 v[42:45], v[138:141], v[172:175], v[42:45]
	v_mfma_f32_16x16x32_bf16 v[38:41], v[130:133], v[180:183], v[38:41]
	v_mfma_f32_16x16x32_bf16 v[34:37], v[138:141], v[180:183], v[34:37]
	v_mfma_f32_16x16x32_bf16 v[66:69], v[134:137], v[160:163], v[66:69]
	v_mfma_f32_16x16x32_bf16 v[58:61], v[142:145], v[160:163], v[58:61]
	v_mfma_f32_16x16x32_bf16 v[54:57], v[134:137], v[168:171], v[54:57]
	v_mfma_f32_16x16x32_bf16 v[50:53], v[142:145], v[168:171], v[50:53]
	v_mfma_f32_16x16x32_bf16 v[46:49], v[134:137], v[176:179], v[46:49]
	v_mfma_f32_16x16x32_bf16 v[42:45], v[142:145], v[176:179], v[42:45]
	v_mfma_f32_16x16x32_bf16 v[38:41], v[134:137], v[152:155], v[38:41]
	v_mfma_f32_16x16x32_bf16 v[34:37], v[142:145], v[152:155], v[34:37]
	v_mfma_f32_16x16x32_bf16 v[28:31], v[184:187], v[156:159], v[28:31]
	v_mfma_f32_16x16x32_bf16 v[24:27], v[196:199], v[156:159], v[24:27]
	v_mfma_f32_16x16x32_bf16 v[20:23], v[184:187], v[164:167], v[20:23]
	v_mfma_f32_16x16x32_bf16 v[16:19], v[196:199], v[164:167], v[16:19]
	v_mfma_f32_16x16x32_bf16 v[12:15], v[184:187], v[172:175], v[12:15]
	v_mfma_f32_16x16x32_bf16 v[8:11], v[196:199], v[172:175], v[8:11]
	v_mfma_f32_16x16x32_bf16 v[4:7], v[184:187], v[180:183], v[4:7]
	v_mfma_f32_16x16x32_bf16 v[0:3], v[196:199], v[180:183], v[0:3]
	v_mfma_f32_16x16x32_bf16 v[28:31], v[188:191], v[160:163], v[28:31]
	v_mfma_f32_16x16x32_bf16 v[24:27], v[148:151], v[160:163], v[24:27]
	v_mfma_f32_16x16x32_bf16 v[20:23], v[188:191], v[168:171], v[20:23]
	v_mfma_f32_16x16x32_bf16 v[16:19], v[148:151], v[168:171], v[16:19]
	v_mfma_f32_16x16x32_bf16 v[12:15], v[188:191], v[176:179], v[12:15]
	v_mfma_f32_16x16x32_bf16 v[8:11], v[148:151], v[176:179], v[8:11]
	v_mfma_f32_16x16x32_bf16 v[4:7], v[188:191], v[152:155], v[4:7]
	v_mfma_f32_16x16x32_bf16 v[0:3], v[148:151], v[152:155], v[0:3]
	s_setprio 0
	s_cmpk_gt_u32 s7, 0xff
	s_barrier
	s_cbranch_scc1 .LBB0_46
	s_barrier
	s_branch .LBB0_46

; __device__ __forceinline__ int otid() { int t = threadIdx.x; asm volatile("" : "+v"(t)); return t; }
;   #define STAGE(P,BASE,LD,br,kt) do{long _g=(long)(br)*LD+(long)(kt)*BK; \
;     _Pragma("unroll") for(int _i=0;_i<2;++_i){ \
;       __builtin_amdgcn_global_load_lds((const unsigned*)(BASE+_g+(long)sR[_i]*LD+sC[_i]), \
;         LDSP(unsigned,(char*)(P)+wid*1024+_i*8192),16,0,0);}}while(0)
;   #define WAIT_V(n) asm volatile("s_waitcnt vmcnt(" #n ")":::"memory")
;   #define BAR __builtin_amdgcn_s_barrier()
; template <class Epi>
; __device__ __forceinline__ void gemm_tile8(const u16* __restrict__ A, long lda, const u16* __restrict__ Bt, long ldb, int K, char* shmc, Epi epi){
;     ...
;   const int tid = otid();
;   int wid=__builtin_amdgcn_readfirstlane(tid>>6),lane=tid&63,wr=wid>>2,wc=wid&3,fr=lane&15,fq=lane>>4;
;   int sR[2], sC[2];
; #pragma unroll
;   for(int i=0;i<2;++i) stage_rc8(wid*1024+lane*16+i*8192, sR[i], sC[i]);
;   const int brow=0, bcol=0;
;   f32x4 acc[2][2][4][2];
; #pragma unroll
;   for(int a=0;a<2;++a)
; #pragma unroll
;     for(int b=0;b<2;++b)
; #pragma unroll
;       for(int m=0;m<4;++m)
; #pragma unroll
;         for(int n=0;n<2;++n) acc[a][b][m][n]=f32x4{0,0,0,0};
;   s16x8 At[4][2],B0[2][2],B1[2][2];
;   int nt=K/BK;
;   STAGE(SB(0,0),Bt,ldb,bcol,0); STAGE(SA(0,0),A,lda,brow,0);
;   STAGE(SB(0,1),Bt,ldb,bcol+HALF,0); STAGE(SA(0,1),A,lda,brow+HALF,0);
;   if(wr==1)BAR;
;   WAIT_V(4); BAR;
.LBB0_959:
	s_lshl_b32 s0, s4, 3
	s_and_b32 s0, s0, 8
	s_bfe_u32 s1, s4, 0x30003
	s_or_b32 s0, s0, s1
	s_lshl_b32 s1, s4, 1
	s_and_b32 s1, s1, 12
	s_bfe_u32 s6, s4, 0x20006
	s_or_b32 s1, s1, s6
	s_and_b32 s6, s4, 0xffffff00
	s_lshl_b32 s1, s1, 4
	s_or_b32 s1, s1, s6
	s_or_b32 s0, s1, s0
	s_cmpk_gt_i32 s0, 0xebf
	s_cbranch_scc1 .LBB0_958
	s_mul_hi_i32 s1, s0, 0x22b63cbf
	s_lshr_b32 s6, s1, 31
	s_ashr_i32 s1, s1, 7
	s_add_i32 s1, s1, s6
	s_lshl_b32 s7, s1, 4
	s_sub_i32 s6, 64, s7
	s_min_i32 s8, s6, 16
	s_abs_i32 s6, s8
	v_cvt_f32_u32_e32 v0, s6
	s_sub_i32 s10, 0, s6
	s_mulk_i32 s1, 0x3b0
	s_sub_i32 s0, s0, s1
	v_rcp_iflag_f32_e32 v0, v0
	s_abs_i32 s1, s0
	s_xor_b32 s9, s0, s8
	s_ashr_i32 s9, s9, 31
	v_mul_f32_e32 v0, 0x4f7ffffe, v0
	v_cvt_u32_f32_e32 v0, v0
	v_mov_b32_e32 v32, v204
	v_readfirstlane_b32 s11, v0
	s_mul_i32 s10, s10, s11
	s_mul_hi_u32 s10, s11, s10
	s_add_i32 s11, s11, s10
	s_mul_hi_u32 s10, s1, s11
	s_mul_i32 s11, s10, s6
	s_sub_i32 s1, s1, s11
	s_add_i32 s12, s10, 1
	s_sub_i32 s11, s1, s6
	s_cmp_ge_u32 s1, s6
	s_cselect_b32 s10, s12, s10
	s_cselect_b32 s1, s11, s1
	s_add_i32 s11, s10, 1
	s_cmp_ge_u32 s1, s6
	s_cselect_b32 s1, s11, s10
	s_xor_b32 s1, s1, s9
	s_sub_i32 s6, s1, s9
	s_mul_i32 s1, s6, s8
	s_sub_i32 s0, s0, s1
	s_add_i32 s0, s0, s7
	s_lshl_b32 s8, s0, 8
	s_ashr_i32 s9, s8, 31
	s_lshl_b64 s[10:11], s[8:9], 13
	s_add_u32 s0, s24, s10
	s_addc_u32 s1, s25, s11
	s_ashr_i32 s7, s6, 31
	s_lshl_b64 s[12:13], s[6:7], 21
	s_add_u32 s14, s2, s12
	v_readfirstlane_b32 s7, v32
	s_addc_u32 s15, s3, s13
	s_ashr_i32 s9, s7, 6
	v_lshlrev_b32_e32 v0, 4, v32
	s_lshl_b32 s16, s9, 10
	v_and_b32_e32 v0, 0x3f0, v0
	s_bfe_i32 s17, s9, 0x10015
	v_or_b32_e32 v1, s16, v0
	s_lshr_b32 s17, s17, 22
	v_add_u32_e32 v0, s17, v1
	v_ashrrev_i32_e32 v2, 10, v0
	v_mul_i32_i24_e32 v0, 0x400, v2
	v_sub_u32_e32 v0, v1, v0
	v_lshrrev_b32_e32 v3, 4, v0
	v_bitop3_b32 v3, v3, v0, 32 bitop3:0x6c
	v_ashrrev_i32_e32 v4, 31, v3
	v_lshrrev_b32_e32 v4, 26, v4
	v_add_u32_e32 v4, v3, v4
	v_ashrrev_i32_e32 v5, 6, v4
	v_and_b32_e32 v4, 0xc0, v4
	v_lshlrev_b32_e32 v0, 3, v2
	v_lshlrev_b32_e32 v2, 5, v2
	v_sub_u32_e32 v3, v3, v4
	v_and_b32_e32 v2, 32, v2
	v_ashrrev_i16_sdwa v3, v215, sext(v3) dst_sel:DWORD dst_unused:UNUSED_PAD src0_sel:DWORD src1_sel:BYTE_0
	v_add_u32_e32 v1, 0x2000, v1
	v_add_u32_sdwa v130, v2, sext(v3) dst_sel:DWORD dst_unused:UNUSED_PAD src0_sel:DWORD src1_sel:WORD_0
	v_ashrrev_i32_e32 v2, 31, v1
	v_lshrrev_b32_e32 v2, 22, v2
	v_add_u32_e32 v2, v1, v2
	v_ashrrev_i32_e32 v2, 10, v2
	v_mul_i32_i24_e32 v3, 0x400, v2
	v_sub_u32_e32 v1, v1, v3
	v_lshrrev_b32_e32 v3, 4, v1
	v_bitop3_b32 v1, v3, v1, 32 bitop3:0x6c
	v_ashrrev_i32_e32 v4, 31, v1
	v_lshrrev_b32_e32 v4, 26, v4
	v_and_b32_e32 v0, -16, v0
	v_lshlrev_b32_e32 v3, 3, v2
	v_add_u32_e32 v4, v1, v4
	v_add_u32_e32 v0, v5, v0
	v_and_b32_e32 v3, -16, v3
	v_ashrrev_i32_e32 v5, 6, v4
	v_add_u32_e32 v6, v5, v3
	v_and_b32_e32 v3, 0xffc0, v4
	v_sub_u32_e32 v1, v1, v3
	v_lshrrev_b16_e32 v3, 7, v1
	v_and_b32_e32 v3, 1, v3
	v_lshlrev_b32_e32 v2, 5, v2
	v_add_u16_e32 v1, v1, v3
	v_and_b32_e32 v2, 32, v2
	v_ashrrev_i16_sdwa v1, v215, sext(v1) dst_sel:DWORD dst_unused:UNUSED_PAD src0_sel:DWORD src1_sel:BYTE_0
	v_add_u32_sdwa v132, v2, sext(v1) dst_sel:DWORD dst_unused:UNUSED_PAD src0_sel:DWORD src1_sel:WORD_0
	v_ashrrev_i32_e32 v1, 31, v0
	v_lshlrev_b64 v[134:135], 13, v[0:1]
	v_ashrrev_i32_e32 v131, 31, v130
	v_ashrrev_i32_e32 v7, 31, v6
	s_add_i32 s17, s16, 0x10000
	v_lshl_add_u64 v[0:1], s[14:15], 0, v[134:135]
	v_lshlrev_b64 v[2:3], 1, v[130:131]
	v_lshlrev_b64 v[136:137], 13, v[6:7]
	v_ashrrev_i32_e32 v133, 31, v132
	s_ashr_i32 s28, s7, 8
	v_lshl_add_u64 v[4:5], v[0:1], 0, v[2:3]
	s_mov_b32 m0, s17
	v_lshl_add_u64 v[6:7], s[14:15], 0, v[136:137]
	v_lshlrev_b64 v[0:1], 1, v[132:133]
	s_add_i32 s18, s16, 0x12000
	s_add_i32 s19, s16, 0x2000
	global_load_lds_dwordx4 v[4:5], off
	v_lshl_add_u64 v[6:7], v[6:7], 0, v[0:1]
	s_mov_b32 m0, s18
	v_lshl_add_u64 v[8:9], s[0:1], 0, v[134:135]
	s_add_u32 s22, s14, 0x100000
	global_load_lds_dwordx4 v[6:7], off
	v_lshl_add_u64 v[10:11], v[8:9], 0, v[2:3]
	s_mov_b32 m0, s16
	v_lshl_add_u64 v[8:9], s[0:1], 0, v[136:137]
	s_addc_u32 s23, s15, 0
	global_load_lds_dwordx4 v[10:11], off
	v_lshl_add_u64 v[8:9], v[8:9], 0, v[0:1]
	s_mov_b32 m0, s19
	s_add_i32 s20, s16, 0x14000
	v_lshl_add_u64 v[12:13], s[22:23], 0, v[134:135]
	global_load_lds_dwordx4 v[8:9], off
	v_lshl_add_u64 v[12:13], v[12:13], 0, v[2:3]
	s_mov_b32 m0, s20
	s_add_i32 s21, s16, 0x16000
	global_load_lds_dwordx4 v[12:13], off
	v_lshl_add_u64 v[12:13], s[22:23], 0, v[136:137]
	s_add_u32 s24, s0, 0x100000
	v_lshl_add_u64 v[12:13], v[12:13], 0, v[0:1]
	s_mov_b32 m0, s21
	s_addc_u32 s25, s1, 0
	global_load_lds_dwordx4 v[12:13], off
	s_add_i32 s22, s16, 0x4000
	v_lshl_add_u64 v[12:13], s[24:25], 0, v[134:135]
	v_lshl_add_u64 v[12:13], v[12:13], 0, v[2:3]
	s_mov_b32 m0, s22
	s_add_i32 s23, s16, 0x6000
	global_load_lds_dwordx4 v[12:13], off
	v_lshl_add_u64 v[12:13], s[24:25], 0, v[136:137]
	v_lshl_add_u64 v[12:13], v[12:13], 0, v[0:1]
	s_mov_b32 m0, s23
	s_cmp_lg_u32 s28, 1
	global_load_lds_dwordx4 v[12:13], off
	s_cbranch_scc1 .LBB0_962
	s_barrier
	s_setprio 1

;   #define STAGE(P,BASE,LD,br,kt) do{long _g=(long)(br)*LD+(long)(kt)*BK; \
;     _Pragma("unroll") for(int _i=0;_i<2;++_i){ \
;       __builtin_amdgcn_global_load_lds((const unsigned*)(BASE+_g+(long)sR[_i]*LD+sC[_i]), \
;         LDSP(unsigned,(char*)(P)+wid*1024+_i*8192),16,0,0);}}while(0)
;   #define LDA(dst,b,h) _Pragma("unroll") for(int m=0;m<4;++m) _Pragma("unroll") for(int k=0;k<2;++k) \
;     dst[m][k]=*reinterpret_cast<const s16x8*>((char*)SA(b,h)+lds_byte8(wr*64+m*16+fr,k*32+fq*8))
;   #define LDB(dst,b,h) _Pragma("unroll") for(int n=0;n<2;++n) _Pragma("unroll") for(int k=0;k<2;++k) \
;     dst[n][k]=*reinterpret_cast<const s16x8*>((char*)SB(b,h)+lds_byte8(wc*32+n*16+fr,k*32+fq*8))
;   #define MMA(ai,bj,At,Bt) do{__builtin_amdgcn_s_setprio(1); \
;     _Pragma("unroll") for(int m=0;m<4;++m) _Pragma("unroll") for(int n=0;n<2;++n) _Pragma("unroll") for(int k=0;k<2;++k) \
;       acc[ai][bj][m][n]=__builtin_amdgcn_mfma_f32_16x16x32_bf16(Bt[n][k],At[m][k],acc[ai][bj][m][n],0,0,0); \
;     __builtin_amdgcn_s_setprio(0);}while(0)
;   #define WAIT_V(n) asm volatile("s_waitcnt vmcnt(" #n ")":::"memory")
;   #define WAIT_L(n) asm volatile("s_waitcnt lgkmcnt(" #n ")":::"memory")
;   #define BAR __builtin_amdgcn_s_barrier()
;   #define SCHED __builtin_amdgcn_sched_barrier(0)
; template <class Epi>
; __device__ __forceinline__ void gemm_tile8(const u16* __restrict__ A, long lda, const u16* __restrict__ Bt, long ldb, int K, char* shmc, Epi epi){
;     ...
;   for(int t=0;t<nt-2;t+=2){
;     LDB(B0,0,0); SCHED; LDA(At,0,0); STAGE(SA(1,1),A,lda,brow+HALF,t+1);
;     WAIT_L(8); BAR; WAIT_L(0); MMA(0,0,At,B0); BAR; SCHED;
;     LDB(B1,0,1); STAGE(SB(0,0),Bt,ldb,bcol,t+2);
;     BAR; WAIT_L(0); MMA(0,1,At,B1); BAR;
;     LDA(At,0,1); STAGE(SA(0,0),A,lda,brow,t+2);
;     BAR; WAIT_L(0); MMA(1,0,At,B0); BAR; SCHED;
;     STAGE(SB(0,1),Bt,ldb,bcol+HALF,t+2);
;     WAIT_V(6); BAR; MMA(1,1,At,B1); BAR;
.LBB0_963:
	ds_read_b128 v[156:159], v152
	ds_read_b128 v[160:163], v152 offset:1024
	ds_read_b128 v[164:167], v152 offset:2048
	ds_read_b128 v[168:171], v152 offset:3072
	v_lshl_add_u64 v[234:235], v[142:143], 0, s[10:11]
	s_add_i32 s31, s16, 0xc000
	v_add_u32_e32 v153, s28, v151
	v_add_u32_e32 v154, s29, v151
	v_add_u32_e32 v155, s30, v151
	v_lshl_add_u64 v[218:219], v[234:235], 0, s[34:35]
	s_mov_b32 m0, s31
	v_lshl_add_u64 v[236:237], v[144:145], 0, s[10:11]
	s_add_i32 s13, s16, 0xe000
	ds_read_b128 v[172:175], v147
	ds_read_b128 v[176:179], v147 offset:1024
	ds_read_b128 v[180:183], v153
	ds_read_b128 v[184:187], v153 offset:1024
	ds_read_b128 v[188:191], v154
	ds_read_b128 v[192:195], v154 offset:1024
	ds_read_b128 v[196:199], v155
	ds_read_b128 v[200:203], v155 offset:1024
	global_load_lds_dwordx4 v[218:219], off
	v_lshl_add_u64 v[218:219], v[236:237], 0, s[34:35]
	s_mov_b32 m0, s13
	s_nop 0
	global_load_lds_dwordx4 v[218:219], off
	s_waitcnt lgkmcnt(8)
	s_barrier
	s_waitcnt lgkmcnt(0)
	s_waitcnt lgkmcnt(0)
	v_mfma_f32_16x16x32_bf16 v[126:129], v[156:159], v[172:175], v[126:129]
	v_mfma_f32_16x16x32_bf16 v[122:125], v[164:167], v[172:175], v[122:125]
	v_mfma_f32_16x16x32_bf16 v[118:121], v[156:159], v[180:183], v[118:121]
	v_mfma_f32_16x16x32_bf16 v[114:117], v[164:167], v[180:183], v[114:117]
	v_mfma_f32_16x16x32_bf16 v[110:113], v[156:159], v[188:191], v[110:113]
	v_mfma_f32_16x16x32_bf16 v[106:109], v[164:167], v[188:191], v[106:109]
	v_mfma_f32_16x16x32_bf16 v[102:105], v[156:159], v[196:199], v[102:105]
	v_mfma_f32_16x16x32_bf16 v[98:101], v[164:167], v[196:199], v[98:101]
	v_mfma_f32_16x16x32_bf16 v[126:129], v[160:163], v[176:179], v[126:129]
	v_mfma_f32_16x16x32_bf16 v[122:125], v[168:171], v[176:179], v[122:125]
	v_mfma_f32_16x16x32_bf16 v[118:121], v[160:163], v[184:187], v[118:121]
	v_mfma_f32_16x16x32_bf16 v[114:117], v[168:171], v[184:187], v[114:117]
	v_mfma_f32_16x16x32_bf16 v[110:113], v[160:163], v[192:195], v[110:113]
	v_mfma_f32_16x16x32_bf16 v[106:109], v[168:171], v[192:195], v[106:109]
	v_mfma_f32_16x16x32_bf16 v[102:105], v[160:163], v[200:203], v[102:105]
	v_mfma_f32_16x16x32_bf16 v[98:101], v[168:171], v[200:203], v[98:101]
	s_barrier
	v_lshl_add_u64 v[238:239], v[138:139], 0, s[10:11]
	s_mov_b32 m0, s17
	v_lshl_add_u64 v[240:241], v[238:239], 0, s[36:37]
	ds_read_b128 v[218:221], v150
	ds_read_b128 v[222:225], v150 offset:1024
	ds_read_b128 v[226:229], v150 offset:2048
	ds_read_b128 v[230:233], v150 offset:3072
	global_load_lds_dwordx4 v[240:241], off
	v_lshl_add_u64 v[240:241], v[140:141], 0, s[10:11]
	v_lshl_add_u64 v[242:243], v[240:241], 0, s[36:37]
	s_mov_b32 m0, s18
	s_nop 0
	global_load_lds_dwordx4 v[242:243], off
	s_barrier
	s_waitcnt lgkmcnt(0)
	s_waitcnt lgkmcnt(0)
	v_mfma_f32_16x16x32_bf16 v[94:97], v[218:221], v[172:175], v[94:97]
	v_mfma_f32_16x16x32_bf16 v[90:93], v[226:229], v[172:175], v[90:93]
	v_mfma_f32_16x16x32_bf16 v[86:89], v[218:221], v[180:183], v[86:89]
	v_mfma_f32_16x16x32_bf16 v[82:85], v[226:229], v[180:183], v[82:85]
	v_mfma_f32_16x16x32_bf16 v[78:81], v[218:221], v[188:191], v[78:81]
	v_mfma_f32_16x16x32_bf16 v[74:77], v[226:229], v[188:191], v[74:77]
	v_mfma_f32_16x16x32_bf16 v[70:73], v[218:221], v[196:199], v[70:73]
	v_mfma_f32_16x16x32_bf16 v[66:69], v[226:229], v[196:199], v[66:69]
	v_mfma_f32_16x16x32_bf16 v[94:97], v[222:225], v[176:179], v[94:97]
	v_mfma_f32_16x16x32_bf16 v[90:93], v[230:233], v[176:179], v[90:93]
	v_mfma_f32_16x16x32_bf16 v[86:89], v[222:225], v[184:187], v[86:89]
	v_mfma_f32_16x16x32_bf16 v[82:85], v[230:233], v[184:187], v[82:85]
	v_mfma_f32_16x16x32_bf16 v[78:81], v[222:225], v[192:195], v[78:81]
	v_mfma_f32_16x16x32_bf16 v[74:77], v[230:233], v[192:195], v[74:77]
	v_mfma_f32_16x16x32_bf16 v[70:73], v[222:225], v[200:203], v[70:73]
	v_mfma_f32_16x16x32_bf16 v[66:69], v[230:233], v[200:203], v[66:69]
	s_mov_b32 m0, s16
	v_lshl_add_u64 v[242:243], v[234:235], 0, s[36:37]
	s_barrier
	ds_read_b128 v[172:175], v147 offset:16384
	ds_read_b128 v[176:179], v147 offset:17408
	ds_read_b128 v[180:183], v153 offset:16384
	ds_read_b128 v[184:187], v153 offset:17408
	ds_read_b128 v[188:191], v154 offset:16384
	ds_read_b128 v[192:195], v154 offset:17408
	ds_read_b128 v[196:199], v155 offset:16384
	ds_read_b128 v[200:203], v155 offset:17408
	global_load_lds_dwordx4 v[242:243], off
	v_lshl_add_u64 v[242:243], v[236:237], 0, s[36:37]
	s_mov_b32 m0, s19
	s_nop 0
	global_load_lds_dwordx4 v[242:243], off
	s_barrier
	s_waitcnt lgkmcnt(0)
	s_waitcnt lgkmcnt(0)
	v_mfma_f32_16x16x32_bf16 v[62:65], v[156:159], v[172:175], v[62:65]
	v_mfma_f32_16x16x32_bf16 v[58:61], v[164:167], v[172:175], v[58:61]
	v_mfma_f32_16x16x32_bf16 v[54:57], v[156:159], v[180:183], v[54:57]
	v_mfma_f32_16x16x32_bf16 v[50:53], v[164:167], v[180:183], v[50:53]
	v_mfma_f32_16x16x32_bf16 v[46:49], v[156:159], v[188:191], v[46:49]
	v_mfma_f32_16x16x32_bf16 v[42:45], v[164:167], v[188:191], v[42:45]
	v_mfma_f32_16x16x32_bf16 v[38:41], v[156:159], v[196:199], v[38:41]
	v_mfma_f32_16x16x32_bf16 v[34:37], v[164:167], v[196:199], v[34:37]
	v_mfma_f32_16x16x32_bf16 v[62:65], v[160:163], v[176:179], v[62:65]
	v_mfma_f32_16x16x32_bf16 v[58:61], v[168:171], v[176:179], v[58:61]
	v_mfma_f32_16x16x32_bf16 v[54:57], v[160:163], v[184:187], v[54:57]
	v_mfma_f32_16x16x32_bf16 v[50:53], v[168:171], v[184:187], v[50:53]
	v_mfma_f32_16x16x32_bf16 v[46:49], v[160:163], v[192:195], v[46:49]
	v_mfma_f32_16x16x32_bf16 v[42:45], v[168:171], v[192:195], v[42:45]
	v_mfma_f32_16x16x32_bf16 v[38:41], v[160:163], v[200:203], v[38:41]
	v_mfma_f32_16x16x32_bf16 v[34:37], v[168:171], v[200:203], v[34:37]
	s_barrier
;   #define STAGE(P,BASE,LD,br,kt) do{long _g=(long)(br)*LD+(long)(kt)*BK; \
;     _Pragma("unroll") for(int _i=0;_i<2;++_i){ \
;       __builtin_amdgcn_global_load_lds((const unsigned*)(BASE+_g+(long)sR[_i]*LD+sC[_i]), \
;         LDSP(unsigned,(char*)(P)+wid*1024+_i*8192),16,0,0);}}while(0)
;   #define LDA(dst,b,h) _Pragma("unroll") for(int m=0;m<4;++m) _Pragma("unroll") for(int k=0;k<2;++k) \
;     dst[m][k]=*reinterpret_cast<const s16x8*>((char*)SA(b,h)+lds_byte8(wr*64+m*16+fr,k*32+fq*8))
;   #define LDB(dst,b,h) _Pragma("unroll") for(int n=0;n<2;++n) _Pragma("unroll") for(int k=0;k<2;++k) \
;     dst[n][k]=*reinterpret_cast<const s16x8*>((char*)SB(b,h)+lds_byte8(wc*32+n*16+fr,k*32+fq*8))
;   #define MMA(ai,bj,At,Bt) do{__builtin_amdgcn_s_setprio(1); \
;     _Pragma("unroll") for(int m=0;m<4;++m) _Pragma("unroll") for(int n=0;n<2;++n) _Pragma("unroll") for(int k=0;k<2;++k) \
;       acc[ai][bj][m][n]=__builtin_amdgcn_mfma_f32_16x16x32_bf16(Bt[n][k],At[m][k],acc[ai][bj][m][n],0,0,0); \
;     __builtin_amdgcn_s_setprio(0);}while(0)
;   #define WAIT_V(n) asm volatile("s_waitcnt vmcnt(" #n ")":::"memory")
;   #define WAIT_L(n) asm volatile("s_waitcnt lgkmcnt(" #n ")":::"memory")
;   #define BAR __builtin_amdgcn_s_barrier()
;   #define SCHED __builtin_amdgcn_sched_barrier(0)
; template <class Epi>
; __device__ __forceinline__ void gemm_tile8(const u16* __restrict__ A, long lda, const u16* __restrict__ Bt, long ldb, int K, char* shmc, Epi epi){
;     ...
;     STAGE(SB(0,1),Bt,ldb,bcol+HALF,t+2);
;     WAIT_V(6); BAR; MMA(1,1,At,B1); BAR;
;     LDB(B0,1,0); SCHED; LDA(At,1,0); STAGE(SA(0,1),A,lda,brow+HALF,t+2);
;     WAIT_L(8); BAR; WAIT_L(0); MMA(0,0,At,B0); BAR; SCHED;
;     LDB(B1,1,1); STAGE(SB(1,0),Bt,ldb,bcol,t+3);
;     BAR; WAIT_L(0); MMA(0,1,At,B1); BAR;
;     LDA(At,1,1); STAGE(SA(1,0),A,lda,brow,t+3);
;     BAR; WAIT_L(0); MMA(1,0,At,B0); BAR; SCHED;
	s_mov_b32 m0, s20
	v_lshl_add_u64 v[156:157], v[238:239], 0, s[38:39]
	global_load_lds_dwordx4 v[156:157], off
	v_lshl_add_u64 v[156:157], v[240:241], 0, s[38:39]
	s_mov_b32 m0, s21
	s_nop 0
	global_load_lds_dwordx4 v[156:157], off
	s_waitcnt vmcnt(6)
	s_barrier
	v_mfma_f32_16x16x32_bf16 v[28:31], v[218:221], v[172:175], v[28:31]
	v_mfma_f32_16x16x32_bf16 v[24:27], v[226:229], v[172:175], v[24:27]
	v_mfma_f32_16x16x32_bf16 v[20:23], v[218:221], v[180:183], v[20:23]
	v_mfma_f32_16x16x32_bf16 v[16:19], v[226:229], v[180:183], v[16:19]
	v_mfma_f32_16x16x32_bf16 v[12:15], v[218:221], v[188:191], v[12:15]
	v_mfma_f32_16x16x32_bf16 v[8:11], v[226:229], v[188:191], v[8:11]
	v_mfma_f32_16x16x32_bf16 v[4:7], v[218:221], v[196:199], v[4:7]
	v_mfma_f32_16x16x32_bf16 v[0:3], v[226:229], v[196:199], v[0:3]
	v_mfma_f32_16x16x32_bf16 v[28:31], v[222:225], v[176:179], v[28:31]
	v_mfma_f32_16x16x32_bf16 v[24:27], v[230:233], v[176:179], v[24:27]
	v_mfma_f32_16x16x32_bf16 v[20:23], v[222:225], v[184:187], v[20:23]
	v_mfma_f32_16x16x32_bf16 v[16:19], v[230:233], v[184:187], v[16:19]
	v_mfma_f32_16x16x32_bf16 v[12:15], v[222:225], v[192:195], v[12:15]
	v_mfma_f32_16x16x32_bf16 v[8:11], v[230:233], v[192:195], v[8:11]
	v_mfma_f32_16x16x32_bf16 v[4:7], v[222:225], v[200:203], v[4:7]
	v_mfma_f32_16x16x32_bf16 v[0:3], v[230:233], v[200:203], v[0:3]
	s_barrier
	ds_read_b128 v[156:159], v149
	ds_read_b128 v[160:163], v149 offset:1024
	ds_read_b128 v[164:167], v149 offset:2048
	ds_read_b128 v[168:171], v149 offset:3072
	s_mov_b32 m0, s22
	v_lshl_add_u64 v[218:219], v[234:235], 0, s[38:39]
	ds_read_b128 v[172:175], v147 offset:32768
	ds_read_b128 v[176:179], v147 offset:33792
	ds_read_b128 v[180:183], v153 offset:32768
	ds_read_b128 v[184:187], v153 offset:33792
	ds_read_b128 v[188:191], v154 offset:32768
	ds_read_b128 v[192:195], v154 offset:33792
	ds_read_b128 v[196:199], v155 offset:32768
	ds_read_b128 v[200:203], v155 offset:33792
	global_load_lds_dwordx4 v[218:219], off
	v_lshl_add_u64 v[218:219], v[236:237], 0, s[38:39]
	s_mov_b32 m0, s23
	s_nop 0
	global_load_lds_dwordx4 v[218:219], off
	s_waitcnt lgkmcnt(8)
	s_barrier
	s_waitcnt lgkmcnt(0)
	s_waitcnt lgkmcnt(0)
	v_mfma_f32_16x16x32_bf16 v[126:129], v[156:159], v[172:175], v[126:129]
	v_mfma_f32_16x16x32_bf16 v[122:125], v[164:167], v[172:175], v[122:125]
	v_mfma_f32_16x16x32_bf16 v[118:121], v[156:159], v[180:183], v[118:121]
	v_mfma_f32_16x16x32_bf16 v[114:117], v[164:167], v[180:183], v[114:117]
	v_mfma_f32_16x16x32_bf16 v[110:113], v[156:159], v[188:191], v[110:113]
	v_mfma_f32_16x16x32_bf16 v[106:109], v[164:167], v[188:191], v[106:109]
	v_mfma_f32_16x16x32_bf16 v[102:105], v[156:159], v[196:199], v[102:105]
	v_mfma_f32_16x16x32_bf16 v[98:101], v[164:167], v[196:199], v[98:101]
	v_mfma_f32_16x16x32_bf16 v[126:129], v[160:163], v[176:179], v[126:129]
	v_mfma_f32_16x16x32_bf16 v[122:125], v[168:171], v[176:179], v[122:125]
	v_mfma_f32_16x16x32_bf16 v[118:121], v[160:163], v[184:187], v[118:121]
	v_mfma_f32_16x16x32_bf16 v[114:117], v[168:171], v[184:187], v[114:117]
	v_mfma_f32_16x16x32_bf16 v[110:113], v[160:163], v[192:195], v[110:113]
	v_mfma_f32_16x16x32_bf16 v[106:109], v[168:171], v[192:195], v[106:109]
	v_mfma_f32_16x16x32_bf16 v[102:105], v[160:163], v[200:203], v[102:105]
	v_mfma_f32_16x16x32_bf16 v[98:101], v[168:171], v[200:203], v[98:101]
	s_barrier
	s_mov_b32 m0, s24
	v_lshl_add_u64 v[242:243], v[238:239], 0, s[40:41]
	ds_read_b128 v[218:221], v148
	ds_read_b128 v[222:225], v148 offset:1024
	ds_read_b128 v[226:229], v148 offset:2048
	ds_read_b128 v[230:233], v148 offset:3072
	global_load_lds_dwordx4 v[242:243], off
	v_lshl_add_u64 v[242:243], v[240:241], 0, s[40:41]
	s_mov_b32 m0, s25
	s_nop 0
	global_load_lds_dwordx4 v[242:243], off
	s_barrier
	s_waitcnt lgkmcnt(0)
	s_waitcnt lgkmcnt(0)
	v_mfma_f32_16x16x32_bf16 v[94:97], v[218:221], v[172:175], v[94:97]
	v_mfma_f32_16x16x32_bf16 v[90:93], v[226:229], v[172:175], v[90:93]
	v_mfma_f32_16x16x32_bf16 v[86:89], v[218:221], v[180:183], v[86:89]
	v_mfma_f32_16x16x32_bf16 v[82:85], v[226:229], v[180:183], v[82:85]
	v_mfma_f32_16x16x32_bf16 v[78:81], v[218:221], v[188:191], v[78:81]
	v_mfma_f32_16x16x32_bf16 v[74:77], v[226:229], v[188:191], v[74:77]
	v_mfma_f32_16x16x32_bf16 v[70:73], v[218:221], v[196:199], v[70:73]
	v_mfma_f32_16x16x32_bf16 v[66:69], v[226:229], v[196:199], v[66:69]
	v_mfma_f32_16x16x32_bf16 v[94:97], v[222:225], v[176:179], v[94:97]
	v_mfma_f32_16x16x32_bf16 v[90:93], v[230:233], v[176:179], v[90:93]
	v_mfma_f32_16x16x32_bf16 v[86:89], v[222:225], v[184:187], v[86:89]
	v_mfma_f32_16x16x32_bf16 v[82:85], v[230:233], v[184:187], v[82:85]
	v_mfma_f32_16x16x32_bf16 v[78:81], v[222:225], v[192:195], v[78:81]
	v_mfma_f32_16x16x32_bf16 v[74:77], v[230:233], v[192:195], v[74:77]
	v_mfma_f32_16x16x32_bf16 v[70:73], v[222:225], v[200:203], v[70:73]
	v_mfma_f32_16x16x32_bf16 v[66:69], v[230:233], v[200:203], v[66:69]
	s_mov_b32 m0, s26
	v_lshl_add_u64 v[234:235], v[234:235], 0, s[40:41]
	s_barrier
	ds_read_b128 v[172:175], v147 offset:49152
	ds_read_b128 v[176:179], v147 offset:50176
	ds_read_b128 v[180:183], v153 offset:49152
	ds_read_b128 v[184:187], v153 offset:50176
	ds_read_b128 v[188:191], v154 offset:49152
	ds_read_b128 v[192:195], v154 offset:50176
	ds_read_b128 v[196:199], v155 offset:49152
	ds_read_b128 v[200:203], v155 offset:50176
	global_load_lds_dwordx4 v[234:235], off
	v_lshl_add_u64 v[234:235], v[236:237], 0, s[40:41]
	s_mov_b32 m0, s27
	s_nop 0
	global_load_lds_dwordx4 v[234:235], off
	s_barrier
;   #define STAGE(P,BASE,LD,br,kt) do{long _g=(long)(br)*LD+(long)(kt)*BK; \
;     _Pragma("unroll") for(int _i=0;_i<2;++_i){ \
;       __builtin_amdgcn_global_load_lds((const unsigned*)(BASE+_g+(long)sR[_i]*LD+sC[_i]), \
;         LDSP(unsigned,(char*)(P)+wid*1024+_i*8192),16,0,0);}}while(0)
;   #define LDA(dst,b,h) _Pragma("unroll") for(int m=0;m<4;++m) _Pragma("unroll") for(int k=0;k<2;++k) \
;     dst[m][k]=*reinterpret_cast<const s16x8*>((char*)SA(b,h)+lds_byte8(wr*64+m*16+fr,k*32+fq*8))
;   #define LDB(dst,b,h) _Pragma("unroll") for(int n=0;n<2;++n) _Pragma("unroll") for(int k=0;k<2;++k) \
;     dst[n][k]=*reinterpret_cast<const s16x8*>((char*)SB(b,h)+lds_byte8(wc*32+n*16+fr,k*32+fq*8))
;   #define MMA(ai,bj,At,Bt) do{__builtin_amdgcn_s_setprio(1); \
;     _Pragma("unroll") for(int m=0;m<4;++m) _Pragma("unroll") for(int n=0;n<2;++n) _Pragma("unroll") for(int k=0;k<2;++k) \
;       acc[ai][bj][m][n]=__builtin_amdgcn_mfma_f32_16x16x32_bf16(Bt[n][k],At[m][k],acc[ai][bj][m][n],0,0,0); \
;     __builtin_amdgcn_s_setprio(0);}while(0)
;   #define WAIT_V(n) asm volatile("s_waitcnt vmcnt(" #n ")":::"memory")
;   #define WAIT_L(n) asm volatile("s_waitcnt lgkmcnt(" #n ")":::"memory")
;   #define BAR __builtin_amdgcn_s_barrier()
; template <class Epi>
; __device__ __forceinline__ void gemm_tile8(const u16* __restrict__ A, long lda, const u16* __restrict__ Bt, long ldb, int K, char* shmc, Epi epi){
;     ...
;     STAGE(SB(1,1),Bt,ldb,bcol+HALF,t+3);
;     WAIT_V(6); BAR; MMA(1,1,At,B1); BAR;
;   }
;   { LDB(B0,0,0); LDA(At,0,0); STAGE(SA(1,1),A,lda,brow+HALF,nt-1);
;     BAR; WAIT_L(0); MMA(0,0,At,B0); BAR;
;     LDB(B1,0,1); BAR; WAIT_L(0); MMA(0,1,At,B1); BAR;
;     LDA(At,0,1); WAIT_V(4); BAR; WAIT_L(0); MMA(1,0,At,B0); MMA(1,1,At,B1); BAR; }
	s_waitcnt lgkmcnt(0)
	s_waitcnt lgkmcnt(0)
	v_mfma_f32_16x16x32_bf16 v[62:65], v[156:159], v[172:175], v[62:65]
	v_mfma_f32_16x16x32_bf16 v[58:61], v[164:167], v[172:175], v[58:61]
	v_mfma_f32_16x16x32_bf16 v[54:57], v[156:159], v[180:183], v[54:57]
	v_mfma_f32_16x16x32_bf16 v[50:53], v[164:167], v[180:183], v[50:53]
	v_mfma_f32_16x16x32_bf16 v[46:49], v[156:159], v[188:191], v[46:49]
	v_mfma_f32_16x16x32_bf16 v[42:45], v[164:167], v[188:191], v[42:45]
	v_mfma_f32_16x16x32_bf16 v[38:41], v[156:159], v[196:199], v[38:41]
	v_mfma_f32_16x16x32_bf16 v[34:37], v[164:167], v[196:199], v[34:37]
	v_mfma_f32_16x16x32_bf16 v[62:65], v[160:163], v[176:179], v[62:65]
	v_mfma_f32_16x16x32_bf16 v[58:61], v[168:171], v[176:179], v[58:61]
	v_mfma_f32_16x16x32_bf16 v[54:57], v[160:163], v[184:187], v[54:57]
	v_mfma_f32_16x16x32_bf16 v[50:53], v[168:171], v[184:187], v[50:53]
	v_mfma_f32_16x16x32_bf16 v[46:49], v[160:163], v[192:195], v[46:49]
	v_mfma_f32_16x16x32_bf16 v[42:45], v[168:171], v[192:195], v[42:45]
	v_mfma_f32_16x16x32_bf16 v[38:41], v[160:163], v[200:203], v[38:41]
	v_mfma_f32_16x16x32_bf16 v[34:37], v[168:171], v[200:203], v[34:37]
	s_barrier
	s_mov_b32 m0, s14
	v_lshl_add_u64 v[156:157], v[238:239], 0, s[42:43]
	global_load_lds_dwordx4 v[156:157], off
	v_lshl_add_u64 v[156:157], v[240:241], 0, s[42:43]
	s_mov_b32 m0, s15
	s_nop 0
	global_load_lds_dwordx4 v[156:157], off
	s_waitcnt vmcnt(6)
	s_barrier
	v_mfma_f32_16x16x32_bf16 v[28:31], v[218:221], v[172:175], v[28:31]
	v_mfma_f32_16x16x32_bf16 v[24:27], v[226:229], v[172:175], v[24:27]
	v_mfma_f32_16x16x32_bf16 v[20:23], v[218:221], v[180:183], v[20:23]
	v_mfma_f32_16x16x32_bf16 v[16:19], v[226:229], v[180:183], v[16:19]
	v_mfma_f32_16x16x32_bf16 v[12:15], v[218:221], v[188:191], v[12:15]
	v_mfma_f32_16x16x32_bf16 v[8:11], v[226:229], v[188:191], v[8:11]
	v_mfma_f32_16x16x32_bf16 v[4:7], v[218:221], v[196:199], v[4:7]
	v_mfma_f32_16x16x32_bf16 v[0:3], v[226:229], v[196:199], v[0:3]
	v_mfma_f32_16x16x32_bf16 v[28:31], v[222:225], v[176:179], v[28:31]
	v_mfma_f32_16x16x32_bf16 v[24:27], v[230:233], v[176:179], v[24:27]
	v_mfma_f32_16x16x32_bf16 v[20:23], v[222:225], v[184:187], v[20:23]
	v_mfma_f32_16x16x32_bf16 v[16:19], v[230:233], v[184:187], v[16:19]
	v_mfma_f32_16x16x32_bf16 v[12:15], v[222:225], v[192:195], v[12:15]
	v_mfma_f32_16x16x32_bf16 v[8:11], v[230:233], v[192:195], v[8:11]
	v_mfma_f32_16x16x32_bf16 v[4:7], v[222:225], v[200:203], v[4:7]
	v_mfma_f32_16x16x32_bf16 v[0:3], v[230:233], v[200:203], v[0:3]
	s_add_i32 s12, s12, 2
	s_add_u32 s10, s10, 0x100
	s_addc_u32 s11, s11, 0
	s_cmp_lt_u32 s12, 60
	s_barrier
	s_cbranch_scc1 .LBB0_963
	s_add_u32 s0, s0, 0x101f80
	s_addc_u32 s1, s1, 0
	v_lshl_add_u64 v[134:135], s[0:1], 0, v[134:135]
	s_mov_b32 m0, s31
	v_lshl_add_u64 v[130:131], v[130:131], 1, v[134:135]
	ds_read_b128 v[138:141], v152
	ds_read_b128 v[142:145], v152 offset:1024
	ds_read_b128 v[156:159], v152 offset:2048
	ds_read_b128 v[160:163], v152 offset:3072
	ds_read_b128 v[164:167], v147
	ds_read_b128 v[168:171], v147 offset:1024
	ds_read_b128 v[172:175], v153
	ds_read_b128 v[176:179], v153 offset:1024
	ds_read_b128 v[180:183], v154
	ds_read_b128 v[184:187], v154 offset:1024
	ds_read_b128 v[188:191], v155
	ds_read_b128 v[192:195], v155 offset:1024
	global_load_lds_dwordx4 v[130:131], off
	v_lshl_add_u64 v[130:131], s[0:1], 0, v[136:137]
	v_lshl_add_u64 v[130:131], v[132:133], 1, v[130:131]
	s_mov_b32 m0, s13
	s_nop 0
	global_load_lds_dwordx4 v[130:131], off
	s_barrier
	s_waitcnt lgkmcnt(0)
	s_waitcnt lgkmcnt(0)
	v_mfma_f32_16x16x32_bf16 v[126:129], v[138:141], v[164:167], v[126:129]
	v_mfma_f32_16x16x32_bf16 v[122:125], v[156:159], v[164:167], v[122:125]
	v_mfma_f32_16x16x32_bf16 v[118:121], v[138:141], v[172:175], v[118:121]
	v_mfma_f32_16x16x32_bf16 v[114:117], v[156:159], v[172:175], v[114:117]
	v_mfma_f32_16x16x32_bf16 v[110:113], v[138:141], v[180:183], v[110:113]
	v_mfma_f32_16x16x32_bf16 v[106:109], v[156:159], v[180:183], v[106:109]
	v_mfma_f32_16x16x32_bf16 v[102:105], v[138:141], v[188:191], v[102:105]
	v_mfma_f32_16x16x32_bf16 v[98:101], v[156:159], v[188:191], v[98:101]
	v_mfma_f32_16x16x32_bf16 v[126:129], v[142:145], v[168:171], v[126:129]
	v_mfma_f32_16x16x32_bf16 v[122:125], v[160:163], v[168:171], v[122:125]
	v_mfma_f32_16x16x32_bf16 v[118:121], v[142:145], v[176:179], v[118:121]
	v_mfma_f32_16x16x32_bf16 v[114:117], v[160:163], v[176:179], v[114:117]
	v_mfma_f32_16x16x32_bf16 v[110:113], v[142:145], v[184:187], v[110:113]
	v_mfma_f32_16x16x32_bf16 v[106:109], v[160:163], v[184:187], v[106:109]
	v_mfma_f32_16x16x32_bf16 v[102:105], v[142:145], v[192:195], v[102:105]
	v_mfma_f32_16x16x32_bf16 v[98:101], v[160:163], v[192:195], v[98:101]
	s_barrier
	ds_read_b128 v[130:133], v150
	ds_read_b128 v[134:137], v150 offset:1024
	ds_read_b128 v[196:199], v150 offset:2048
	ds_read_b128 v[200:203], v150 offset:3072
	s_barrier
	s_waitcnt lgkmcnt(0)
	s_waitcnt lgkmcnt(0)
	v_mfma_f32_16x16x32_bf16 v[94:97], v[130:133], v[164:167], v[94:97]
	v_mfma_f32_16x16x32_bf16 v[90:93], v[196:199], v[164:167], v[90:93]
	v_mfma_f32_16x16x32_bf16 v[86:89], v[130:133], v[172:175], v[86:89]
	v_mfma_f32_16x16x32_bf16 v[82:85], v[196:199], v[172:175], v[82:85]
	v_mfma_f32_16x16x32_bf16 v[78:81], v[130:133], v[180:183], v[78:81]
	v_mfma_f32_16x16x32_bf16 v[74:77], v[196:199], v[180:183], v[74:77]
	v_mfma_f32_16x16x32_bf16 v[70:73], v[130:133], v[188:191], v[70:73]
	v_mfma_f32_16x16x32_bf16 v[66:69], v[196:199], v[188:191], v[66:69]
	v_mfma_f32_16x16x32_bf16 v[94:97], v[134:137], v[168:171], v[94:97]
	v_mfma_f32_16x16x32_bf16 v[90:93], v[200:203], v[168:171], v[90:93]
	v_mfma_f32_16x16x32_bf16 v[86:89], v[134:137], v[176:179], v[86:89]
	v_mfma_f32_16x16x32_bf16 v[82:85], v[200:203], v[176:179], v[82:85]
	v_mfma_f32_16x16x32_bf16 v[78:81], v[134:137], v[184:187], v[78:81]
	v_mfma_f32_16x16x32_bf16 v[74:77], v[200:203], v[184:187], v[74:77]
	v_mfma_f32_16x16x32_bf16 v[70:73], v[134:137], v[192:195], v[70:73]
	v_mfma_f32_16x16x32_bf16 v[66:69], v[200:203], v[192:195], v[66:69]
	s_barrier
;   #define LDA(dst,b,h) _Pragma("unroll") for(int m=0;m<4;++m) _Pragma("unroll") for(int k=0;k<2;++k) \
;     dst[m][k]=*reinterpret_cast<const s16x8*>((char*)SA(b,h)+lds_byte8(wr*64+m*16+fr,k*32+fq*8))
;   #define LDB(dst,b,h) _Pragma("unroll") for(int n=0;n<2;++n) _Pragma("unroll") for(int k=0;k<2;++k) \
;     dst[n][k]=*reinterpret_cast<const s16x8*>((char*)SB(b,h)+lds_byte8(wc*32+n*16+fr,k*32+fq*8))
;   #define MMA(ai,bj,At,Bt) do{__builtin_amdgcn_s_setprio(1); \
;     _Pragma("unroll") for(int m=0;m<4;++m) _Pragma("unroll") for(int n=0;n<2;++n) _Pragma("unroll") for(int k=0;k<2;++k) \
;       acc[ai][bj][m][n]=__builtin_amdgcn_mfma_f32_16x16x32_bf16(Bt[n][k],At[m][k],acc[ai][bj][m][n],0,0,0); \
;     __builtin_amdgcn_s_setprio(0);}while(0)
;   #define WAIT_V(n) asm volatile("s_waitcnt vmcnt(" #n ")":::"memory")
;   #define WAIT_L(n) asm volatile("s_waitcnt lgkmcnt(" #n ")":::"memory")
;   #define BAR __builtin_amdgcn_s_barrier()
; template <class Epi>
; __device__ __forceinline__ void gemm_tile8(const u16* __restrict__ A, long lda, const u16* __restrict__ Bt, long ldb, int K, char* shmc, Epi epi){
;     ...
;     LDA(At,0,1); WAIT_V(4); BAR; WAIT_L(0); MMA(1,0,At,B0); MMA(1,1,At,B1); BAR; }
;   { LDB(B0,1,0); LDA(At,1,0); WAIT_V(2); BAR; WAIT_L(0); MMA(0,0,At,B0); BAR;
;     LDB(B1,1,1); WAIT_V(0); BAR; WAIT_L(0); MMA(0,1,At,B1); BAR;
	ds_read_b128 v[164:167], v147 offset:16384
	ds_read_b128 v[168:171], v147 offset:17408
	ds_read_b128 v[172:175], v153 offset:16384
	ds_read_b128 v[176:179], v153 offset:17408
	ds_read_b128 v[180:183], v154 offset:16384
	ds_read_b128 v[184:187], v154 offset:17408
	ds_read_b128 v[188:191], v155 offset:16384
	ds_read_b128 v[192:195], v155 offset:17408
	s_waitcnt vmcnt(4)
	s_barrier
	s_waitcnt lgkmcnt(0)
	s_waitcnt lgkmcnt(0)
	v_mfma_f32_16x16x32_bf16 v[62:65], v[138:141], v[164:167], v[62:65]
	v_mfma_f32_16x16x32_bf16 v[58:61], v[156:159], v[164:167], v[58:61]
	v_mfma_f32_16x16x32_bf16 v[54:57], v[138:141], v[172:175], v[54:57]
	v_mfma_f32_16x16x32_bf16 v[50:53], v[156:159], v[172:175], v[50:53]
	v_mfma_f32_16x16x32_bf16 v[46:49], v[138:141], v[180:183], v[46:49]
	v_mfma_f32_16x16x32_bf16 v[42:45], v[156:159], v[180:183], v[42:45]
	v_mfma_f32_16x16x32_bf16 v[38:41], v[138:141], v[188:191], v[38:41]
	v_mfma_f32_16x16x32_bf16 v[34:37], v[156:159], v[188:191], v[34:37]
	v_mfma_f32_16x16x32_bf16 v[62:65], v[142:145], v[168:171], v[62:65]
	v_mfma_f32_16x16x32_bf16 v[58:61], v[160:163], v[168:171], v[58:61]
	v_mfma_f32_16x16x32_bf16 v[54:57], v[142:145], v[176:179], v[54:57]
	v_mfma_f32_16x16x32_bf16 v[50:53], v[160:163], v[176:179], v[50:53]
	v_mfma_f32_16x16x32_bf16 v[46:49], v[142:145], v[184:187], v[46:49]
	v_mfma_f32_16x16x32_bf16 v[42:45], v[160:163], v[184:187], v[42:45]
	v_mfma_f32_16x16x32_bf16 v[38:41], v[142:145], v[192:195], v[38:41]
	v_mfma_f32_16x16x32_bf16 v[34:37], v[160:163], v[192:195], v[34:37]
	v_mfma_f32_16x16x32_bf16 v[28:31], v[130:133], v[164:167], v[28:31]
	v_mfma_f32_16x16x32_bf16 v[24:27], v[196:199], v[164:167], v[24:27]
	v_mfma_f32_16x16x32_bf16 v[20:23], v[130:133], v[172:175], v[20:23]
	v_mfma_f32_16x16x32_bf16 v[16:19], v[196:199], v[172:175], v[16:19]
	v_mfma_f32_16x16x32_bf16 v[12:15], v[130:133], v[180:183], v[12:15]
	v_mfma_f32_16x16x32_bf16 v[8:11], v[196:199], v[180:183], v[8:11]
	v_mfma_f32_16x16x32_bf16 v[4:7], v[130:133], v[188:191], v[4:7]
	v_mfma_f32_16x16x32_bf16 v[0:3], v[196:199], v[188:191], v[0:3]
	v_mfma_f32_16x16x32_bf16 v[28:31], v[134:137], v[168:171], v[28:31]
	v_mfma_f32_16x16x32_bf16 v[24:27], v[200:203], v[168:171], v[24:27]
	v_mfma_f32_16x16x32_bf16 v[20:23], v[134:137], v[176:179], v[20:23]
	v_mfma_f32_16x16x32_bf16 v[16:19], v[200:203], v[176:179], v[16:19]
	v_mfma_f32_16x16x32_bf16 v[12:15], v[134:137], v[184:187], v[12:15]
	v_mfma_f32_16x16x32_bf16 v[8:11], v[200:203], v[184:187], v[8:11]
	v_mfma_f32_16x16x32_bf16 v[4:7], v[134:137], v[192:195], v[4:7]
	v_mfma_f32_16x16x32_bf16 v[0:3], v[200:203], v[192:195], v[0:3]
	s_barrier
	ds_read_b128 v[130:133], v149
	ds_read_b128 v[134:137], v149 offset:1024
	ds_read_b128 v[138:141], v149 offset:2048
	ds_read_b128 v[142:145], v149 offset:3072
	ds_read_b128 v[156:159], v147 offset:32768
	ds_read_b128 v[160:163], v147 offset:33792
	ds_read_b128 v[164:167], v153 offset:32768
	ds_read_b128 v[168:171], v153 offset:33792
	ds_read_b128 v[172:175], v154 offset:32768
	ds_read_b128 v[176:179], v154 offset:33792
	ds_read_b128 v[180:183], v155 offset:32768
	ds_read_b128 v[184:187], v155 offset:33792
	s_waitcnt vmcnt(2)
	s_barrier
	s_waitcnt lgkmcnt(0)
	s_waitcnt lgkmcnt(0)
	v_mfma_f32_16x16x32_bf16 v[126:129], v[130:133], v[156:159], v[126:129]
	v_mfma_f32_16x16x32_bf16 v[122:125], v[138:141], v[156:159], v[122:125]
	v_mfma_f32_16x16x32_bf16 v[118:121], v[130:133], v[164:167], v[118:121]
	v_mfma_f32_16x16x32_bf16 v[114:117], v[138:141], v[164:167], v[114:117]
	v_mfma_f32_16x16x32_bf16 v[110:113], v[130:133], v[172:175], v[110:113]
	v_mfma_f32_16x16x32_bf16 v[106:109], v[138:141], v[172:175], v[106:109]
	v_mfma_f32_16x16x32_bf16 v[102:105], v[130:133], v[180:183], v[102:105]
	v_mfma_f32_16x16x32_bf16 v[98:101], v[138:141], v[180:183], v[98:101]
	v_mfma_f32_16x16x32_bf16 v[126:129], v[134:137], v[160:163], v[126:129]
	v_mfma_f32_16x16x32_bf16 v[122:125], v[142:145], v[160:163], v[122:125]
	v_mfma_f32_16x16x32_bf16 v[118:121], v[134:137], v[168:171], v[118:121]
	v_mfma_f32_16x16x32_bf16 v[114:117], v[142:145], v[168:171], v[114:117]
	v_mfma_f32_16x16x32_bf16 v[110:113], v[134:137], v[176:179], v[110:113]
	v_mfma_f32_16x16x32_bf16 v[106:109], v[142:145], v[176:179], v[106:109]
	v_mfma_f32_16x16x32_bf16 v[102:105], v[134:137], v[184:187], v[102:105]
	v_mfma_f32_16x16x32_bf16 v[98:101], v[142:145], v[184:187], v[98:101]
	s_barrier
;   #define LDA(dst,b,h) _Pragma("unroll") for(int m=0;m<4;++m) _Pragma("unroll") for(int k=0;k<2;++k) \
;     dst[m][k]=*reinterpret_cast<const s16x8*>((char*)SA(b,h)+lds_byte8(wr*64+m*16+fr,k*32+fq*8))
;   #define LDB(dst,b,h) _Pragma("unroll") for(int n=0;n<2;++n) _Pragma("unroll") for(int k=0;k<2;++k) \
;     dst[n][k]=*reinterpret_cast<const s16x8*>((char*)SB(b,h)+lds_byte8(wc*32+n*16+fr,k*32+fq*8))
;   #define MMA(ai,bj,At,Bt) do{__builtin_amdgcn_s_setprio(1); \
;     _Pragma("unroll") for(int m=0;m<4;++m) _Pragma("unroll") for(int n=0;n<2;++n) _Pragma("unroll") for(int k=0;k<2;++k) \
;       acc[ai][bj][m][n]=__builtin_amdgcn_mfma_f32_16x16x32_bf16(Bt[n][k],At[m][k],acc[ai][bj][m][n],0,0,0); \
;     __builtin_amdgcn_s_setprio(0);}while(0)
;   #define WAIT_V(n) asm volatile("s_waitcnt vmcnt(" #n ")":::"memory")
;   #define WAIT_L(n) asm volatile("s_waitcnt lgkmcnt(" #n ")":::"memory")
;   #define BAR __builtin_amdgcn_s_barrier()
; template <class Epi>
; __device__ __forceinline__ void gemm_tile8(const u16* __restrict__ A, long lda, const u16* __restrict__ Bt, long ldb, int K, char* shmc, Epi epi){
;     ...
;   { LDB(B0,1,0); LDA(At,1,0); WAIT_V(2); BAR; WAIT_L(0); MMA(0,0,At,B0); BAR;
;     LDB(B1,1,1); WAIT_V(0); BAR; WAIT_L(0); MMA(0,1,At,B1); BAR;
;     LDA(At,1,1); BAR; WAIT_L(0); MMA(1,0,At,B0); MMA(1,1,At,B1); BAR; }
;   if(wr==0)BAR;
	ds_read_b128 v[188:191], v148
	ds_read_b128 v[192:195], v148 offset:1024
	ds_read_b128 v[196:199], v148 offset:2048
	ds_read_b128 v[148:151], v148 offset:3072
	s_waitcnt vmcnt(0)
	s_barrier
	s_waitcnt lgkmcnt(0)
	s_waitcnt lgkmcnt(0)
	v_mfma_f32_16x16x32_bf16 v[94:97], v[188:191], v[156:159], v[94:97]
	v_mfma_f32_16x16x32_bf16 v[90:93], v[196:199], v[156:159], v[90:93]
	v_mfma_f32_16x16x32_bf16 v[86:89], v[188:191], v[164:167], v[86:89]
	v_mfma_f32_16x16x32_bf16 v[82:85], v[196:199], v[164:167], v[82:85]
	v_mfma_f32_16x16x32_bf16 v[78:81], v[188:191], v[172:175], v[78:81]
	v_mfma_f32_16x16x32_bf16 v[74:77], v[196:199], v[172:175], v[74:77]
	v_mfma_f32_16x16x32_bf16 v[70:73], v[188:191], v[180:183], v[70:73]
	v_mfma_f32_16x16x32_bf16 v[66:69], v[196:199], v[180:183], v[66:69]
	v_mfma_f32_16x16x32_bf16 v[94:97], v[192:195], v[160:163], v[94:97]
	v_mfma_f32_16x16x32_bf16 v[90:93], v[148:151], v[160:163], v[90:93]
	v_mfma_f32_16x16x32_bf16 v[86:89], v[192:195], v[168:171], v[86:89]
	v_mfma_f32_16x16x32_bf16 v[82:85], v[148:151], v[168:171], v[82:85]
	v_mfma_f32_16x16x32_bf16 v[78:81], v[192:195], v[176:179], v[78:81]
	v_mfma_f32_16x16x32_bf16 v[74:77], v[148:151], v[176:179], v[74:77]
	v_mfma_f32_16x16x32_bf16 v[70:73], v[192:195], v[184:187], v[70:73]
	v_mfma_f32_16x16x32_bf16 v[66:69], v[148:151], v[184:187], v[66:69]
	s_barrier
	ds_read_b128 v[156:159], v147 offset:49152
	ds_read_b128 v[160:163], v147 offset:50176
	ds_read_b128 v[164:167], v153 offset:49152
	ds_read_b128 v[168:171], v153 offset:50176
	ds_read_b128 v[172:175], v154 offset:49152
	ds_read_b128 v[176:179], v154 offset:50176
	ds_read_b128 v[180:183], v155 offset:49152
	ds_read_b128 v[152:155], v155 offset:50176
	s_barrier
	s_waitcnt lgkmcnt(0)
	s_waitcnt lgkmcnt(0)
	v_mfma_f32_16x16x32_bf16 v[62:65], v[130:133], v[156:159], v[62:65]
	v_mfma_f32_16x16x32_bf16 v[58:61], v[138:141], v[156:159], v[58:61]
	v_mfma_f32_16x16x32_bf16 v[54:57], v[130:133], v[164:167], v[54:57]
	v_mfma_f32_16x16x32_bf16 v[50:53], v[138:141], v[164:167], v[50:53]
	v_mfma_f32_16x16x32_bf16 v[46:49], v[130:133], v[172:175], v[46:49]
	v_mfma_f32_16x16x32_bf16 v[42:45], v[138:141], v[172:175], v[42:45]
	v_mfma_f32_16x16x32_bf16 v[38:41], v[130:133], v[180:183], v[38:41]
	v_mfma_f32_16x16x32_bf16 v[34:37], v[138:141], v[180:183], v[34:37]
	v_mfma_f32_16x16x32_bf16 v[62:65], v[134:137], v[160:163], v[62:65]
	v_mfma_f32_16x16x32_bf16 v[58:61], v[142:145], v[160:163], v[58:61]
	v_mfma_f32_16x16x32_bf16 v[54:57], v[134:137], v[168:171], v[54:57]
	v_mfma_f32_16x16x32_bf16 v[50:53], v[142:145], v[168:171], v[50:53]
	v_mfma_f32_16x16x32_bf16 v[46:49], v[134:137], v[176:179], v[46:49]
	v_mfma_f32_16x16x32_bf16 v[42:45], v[142:145], v[176:179], v[42:45]
	v_mfma_f32_16x16x32_bf16 v[38:41], v[134:137], v[152:155], v[38:41]
	v_mfma_f32_16x16x32_bf16 v[34:37], v[142:145], v[152:155], v[34:37]
	v_mfma_f32_16x16x32_bf16 v[28:31], v[188:191], v[156:159], v[28:31]
	v_mfma_f32_16x16x32_bf16 v[24:27], v[196:199], v[156:159], v[24:27]
	v_mfma_f32_16x16x32_bf16 v[20:23], v[188:191], v[164:167], v[20:23]
	v_mfma_f32_16x16x32_bf16 v[16:19], v[196:199], v[164:167], v[16:19]
	v_mfma_f32_16x16x32_bf16 v[12:15], v[188:191], v[172:175], v[12:15]
	v_mfma_f32_16x16x32_bf16 v[8:11], v[196:199], v[172:175], v[8:11]
	v_mfma_f32_16x16x32_bf16 v[4:7], v[188:191], v[180:183], v[4:7]
	v_mfma_f32_16x16x32_bf16 v[0:3], v[196:199], v[180:183], v[0:3]
	v_mfma_f32_16x16x32_bf16 v[28:31], v[192:195], v[160:163], v[28:31]
	v_mfma_f32_16x16x32_bf16 v[24:27], v[148:151], v[160:163], v[24:27]
	v_mfma_f32_16x16x32_bf16 v[20:23], v[192:195], v[168:171], v[20:23]
	v_mfma_f32_16x16x32_bf16 v[16:19], v[148:151], v[168:171], v[16:19]
	v_mfma_f32_16x16x32_bf16 v[12:15], v[192:195], v[176:179], v[12:15]
	v_mfma_f32_16x16x32_bf16 v[8:11], v[148:151], v[176:179], v[8:11]
	v_mfma_f32_16x16x32_bf16 v[4:7], v[192:195], v[152:155], v[4:7]
	v_mfma_f32_16x16x32_bf16 v[0:3], v[148:151], v[152:155], v[0:3]
	s_setprio 0
	s_cmpk_gt_u32 s7, 0xff
	s_barrier
	s_cbranch_scc1 .LBB0_966
	s_barrier
